# best + the two pre-barrier waits merged into one s_waitcnt vmcnt(N) lgkmcnt(0) in every K-loop load segment
# baseline (speedup 1.0000x reference)
; #define PG8_STAGE(bufoff, gbase, voff) do { _Pragma("unroll") for (int _i = 0; _i < 2; ++_i) \
;         __builtin_amdgcn_global_load_lds((const unsigned*)((const char*)(gbase) + (voff)[_i]), (PG8_LAS unsigned*)(lds + (bufoff) + ldsw + _i * 8192), 16, 0, 0); } while (0)
; #define PG8_LDA(dst, b, h) do { _Pragma("unroll") for (int m = 0; m < 4; ++m) _Pragma("unroll") for (int k = 0; k < 2; ++k) dst[m][k] = *(const PG8_LAS bf16x8*)(lds + PG8_SA(b, h) + aoff + m * 2048 + k * 1024); } while (0)
; #define PG8_LDB(dst, b, h) do { _Pragma("unroll") for (int n = 0; n < 2; ++n) _Pragma("unroll") for (int k = 0; k < 2; ++k) dst[n][k] = *(const PG8_LAS bf16x8*)(lds + PG8_SB(b, h) + boff + n * 2048 + k * 1024); } while (0)
; #define PG8_WAIT_V(n) asm volatile("s_waitcnt vmcnt(" #n ")" ::: "memory")
; #define PG8_WAIT_L(n) asm volatile("s_waitcnt lgkmcnt(" #n ")" ::: "memory")
; #define PG8_BAR __builtin_amdgcn_s_barrier()
; #define PG8_SCHED __builtin_amdgcn_sched_barrier(0)
; template <class Epi, class Sched, bool ALIGN_EPI = false, bool SP2 = false>
; __device__ __forceinline__ void gemm_phase(PG8_LAS unsigned char* lds, const Gemm g, const Sched& S, const Epi& E) {
;     ...
;         const char* nA = has_next ? (const char*)g.A + (size_t)nxt.pm * tstep : cA; const char* nB = has_next ? (const char*)g.Bt + (size_t)nxt.pn * tstep : cB;
;         for (int t = 0; t < nt; t += 2) {
;             const bool last = (t == nt - 2);
;             const char* a1 = cA + (size_t)(t + 1) * kstepA;
;             const char* a2 = last ? nA : cA + (size_t)(t + 2) * kstepA; const char* b2 = last ? nB : cB + (size_t)(t + 2) * kstep;
;             const char* a3 = a2 + kstepA; const char* b3 = b2 + kstep;
;             if (last && has_next) S.a_ready(nxt);
;             if constexpr (SP2) {
;             PG8_LDB(B0, 0, 0); PG8_LDB(B1, 0, 1); PG8_SCHED; PG8_LDA(At, 0, 0); PG8_STAGE(PG8_SA(1, 1), a1 + hstep, voffA);
;             PG8_WAIT_V(8); PG8_WAIT_L(0); PG8_BAR; PG8_MMA(0, 0, At, B0); PG8_MMA(0, 1, At, B1); PG8_BAR; PG8_SCHED;
;             PG8_LDA(At, 0, 1); PG8_STAGE(PG8_SB(0, 0), b2, voffB); PG8_STAGE(PG8_SB(0, 1), b2 + hstep, voffB); PG8_STAGE(PG8_SA(0, 0), a2, voffA);
;             PG8_WAIT_V(8); PG8_WAIT_L(0); PG8_BAR; PG8_MMA(1, 0, At, B0); PG8_MMA(1, 1, At, B1); PG8_BAR; PG8_SCHED;
.LBB0_237:
	s_ashr_i32 s11, s10, 31
	s_lshl_b64 s[2:3], s[10:11], 19
	s_add_u32 s12, s52, s2
	s_addc_u32 s13, s53, s3
	s_and_b64 s[2:3], s[40:41], exec
	s_cselect_b32 s11, s13, s25
	s_cselect_b32 s67, s12, s24
	s_ashr_i32 s9, s8, 31
	s_lshl_b64 s[2:3], s[8:9], 19
	s_add_u32 s44, s54, s2
	s_addc_u32 s45, s55, s3
	s_and_b64 s[2:3], s[40:41], exec
	s_cselect_b32 s9, s45, s27
	s_cselect_b32 s68, s44, s26
	s_add_u32 s69, s26, 0x100
	s_addc_u32 s70, s27, 0
	s_mov_b32 s71, -2
	s_add_u32 s2, s24, 0x8000
	s_addc_u32 s3, s25, 0
	s_cmp_eq_u32 s71, 12
	s_cselect_b32 s46, s67, s2
	s_cselect_b32 s47, s11, s3
	s_cselect_b32 s42, s68, s69
	s_cselect_b32 s43, s9, s70
	s_add_u32 s26, s46, 0x4000
	s_addc_u32 s27, s47, 0
	v_add_u32_e32 v148, s76, v150
	s_add_i32 s72, 0, 0x14000
	ds_read_b128 v[144:147], v148
	ds_read_b128 v[160:163], v148 offset:1024
	ds_read_b128 v[164:167], v148 offset:2048
	ds_read_b128 v[168:171], v148 offset:3072
	v_add_u32_e32 v148, s72, v150
	ds_read_b128 v[172:175], v148
	ds_read_b128 v[176:179], v148 offset:1024
	ds_read_b128 v[180:183], v148 offset:2048
	ds_read_b128 v[184:187], v148 offset:3072
	v_lshl_add_u64 v[148:149], s[24:25], 0, v[142:143]
	s_add_i32 m0, s23, 0xc000
	ds_read_b128 v[188:191], v152
	ds_read_b128 v[206:209], v152 offset:1024
	ds_read_b128 v[210:213], v152 offset:2048
	ds_read_b128 v[214:217], v152 offset:3072
	ds_read_b128 v[218:221], v152 offset:4096
	ds_read_b128 v[222:225], v152 offset:5120
	ds_read_b128 v[226:229], v152 offset:6144
	ds_read_b128 v[230:233], v152 offset:7168
	global_load_lds_dwordx4 v[148:149], off
	v_lshl_add_u64 v[148:149], s[24:25], 0, v[140:141]
	s_add_i32 m0, s23, 0xe000
	s_nop 0
	global_load_lds_dwordx4 v[148:149], off
	s_waitcnt vmcnt(8) lgkmcnt(0)
	s_barrier
	v_mfma_f32_16x16x32_bf16 v[126:129], v[144:147], v[188:191], 0
	v_mfma_f32_16x16x32_bf16 v[126:129], v[160:163], v[206:209], v[126:129]
	v_mfma_f32_16x16x32_bf16 v[122:125], v[168:171], v[206:209], 0
	v_mfma_f32_16x16x32_bf16 v[122:125], v[164:167], v[188:191], v[122:125]
	v_mfma_f32_16x16x32_bf16 v[106:109], v[164:167], v[210:213], 0
	v_mfma_f32_16x16x32_bf16 v[106:109], v[168:171], v[214:217], v[106:109]
	v_mfma_f32_16x16x32_bf16 v[110:113], v[160:163], v[214:217], 0
	v_mfma_f32_16x16x32_bf16 v[110:113], v[144:147], v[210:213], v[110:113]
	v_mfma_f32_16x16x32_bf16 v[94:97], v[144:147], v[218:221], 0
	v_mfma_f32_16x16x32_bf16 v[94:97], v[160:163], v[222:225], v[94:97]
	v_mfma_f32_16x16x32_bf16 v[90:93], v[168:171], v[222:225], 0
	v_mfma_f32_16x16x32_bf16 v[90:93], v[164:167], v[218:221], v[90:93]
	v_mfma_f32_16x16x32_bf16 v[74:77], v[164:167], v[226:229], 0
	v_mfma_f32_16x16x32_bf16 v[74:77], v[168:171], v[230:233], v[74:77]
	v_mfma_f32_16x16x32_bf16 v[78:81], v[160:163], v[230:233], 0
	v_mfma_f32_16x16x32_bf16 v[78:81], v[144:147], v[226:229], v[78:81]
	v_mfma_f32_16x16x32_bf16 v[118:121], v[172:175], v[188:191], 0
	v_mfma_f32_16x16x32_bf16 v[118:121], v[176:179], v[206:209], v[118:121]
	v_mfma_f32_16x16x32_bf16 v[114:117], v[184:187], v[206:209], 0
	v_mfma_f32_16x16x32_bf16 v[114:117], v[180:183], v[188:191], v[114:117]
	v_mfma_f32_16x16x32_bf16 v[98:101], v[180:183], v[210:213], 0
	v_mfma_f32_16x16x32_bf16 v[98:101], v[184:187], v[214:217], v[98:101]
	v_mfma_f32_16x16x32_bf16 v[102:105], v[176:179], v[214:217], 0
	v_mfma_f32_16x16x32_bf16 v[102:105], v[172:175], v[210:213], v[102:105]
	v_mfma_f32_16x16x32_bf16 v[86:89], v[172:175], v[218:221], 0
	v_mfma_f32_16x16x32_bf16 v[86:89], v[176:179], v[222:225], v[86:89]
	v_mfma_f32_16x16x32_bf16 v[82:85], v[184:187], v[222:225], 0
	v_mfma_f32_16x16x32_bf16 v[82:85], v[180:183], v[218:221], v[82:85]
	v_mfma_f32_16x16x32_bf16 v[66:69], v[180:183], v[226:229], 0
	v_mfma_f32_16x16x32_bf16 v[66:69], v[184:187], v[230:233], v[66:69]
	v_mfma_f32_16x16x32_bf16 v[70:73], v[176:179], v[230:233], 0
	v_mfma_f32_16x16x32_bf16 v[70:73], v[172:175], v[226:229], v[70:73]
	s_barrier
	s_add_i32 s24, s76, s51
	v_lshl_add_u64 v[148:149], s[42:43], 0, v[132:133]
	s_mov_b32 m0, s24
	ds_read_b128 v[188:191], v152 offset:16384
	ds_read_b128 v[206:209], v152 offset:17408
	ds_read_b128 v[210:213], v152 offset:18432
	ds_read_b128 v[214:217], v152 offset:19456
	ds_read_b128 v[218:221], v152 offset:20480
	ds_read_b128 v[222:225], v152 offset:21504
	ds_read_b128 v[226:229], v152 offset:22528
	ds_read_b128 v[230:233], v152 offset:23552
	global_load_lds_dwordx4 v[148:149], off
	s_add_i32 m0, s24, 0x2000
	s_add_u32 s24, s42, 0x40000
	v_lshl_add_u64 v[234:235], s[42:43], 0, v[136:137]
	s_addc_u32 s25, s43, 0
	s_add_i32 s72, s72, s51
	global_load_lds_dwordx4 v[234:235], off
	v_lshl_add_u64 v[236:237], s[24:25], 0, v[132:133]
	s_mov_b32 m0, s72
	s_nop 0
	global_load_lds_dwordx4 v[236:237], off
	v_lshl_add_u64 v[236:237], s[24:25], 0, v[136:137]
	s_add_i32 m0, s72, 0x2000
	s_nop 0
	global_load_lds_dwordx4 v[236:237], off
	v_lshl_add_u64 v[236:237], s[46:47], 0, v[130:131]
	s_mov_b32 m0, s23
	s_nop 0
	global_load_lds_dwordx4 v[236:237], off
	v_lshl_add_u64 v[236:237], s[46:47], 0, v[134:135]
	s_mov_b32 m0, s56
	s_nop 0
	global_load_lds_dwordx4 v[236:237], off
	s_waitcnt vmcnt(8) lgkmcnt(0)
	s_barrier
; #define PG8_STAGE(bufoff, gbase, voff) do { _Pragma("unroll") for (int _i = 0; _i < 2; ++_i) \
;         __builtin_amdgcn_global_load_lds((const unsigned*)((const char*)(gbase) + (voff)[_i]), (PG8_LAS unsigned*)(lds + (bufoff) + ldsw + _i * 8192), 16, 0, 0); } while (0)
; #define PG8_LDA(dst, b, h) do { _Pragma("unroll") for (int m = 0; m < 4; ++m) _Pragma("unroll") for (int k = 0; k < 2; ++k) dst[m][k] = *(const PG8_LAS bf16x8*)(lds + PG8_SA(b, h) + aoff + m * 2048 + k * 1024); } while (0)
; #define PG8_LDB(dst, b, h) do { _Pragma("unroll") for (int n = 0; n < 2; ++n) _Pragma("unroll") for (int k = 0; k < 2; ++k) dst[n][k] = *(const PG8_LAS bf16x8*)(lds + PG8_SB(b, h) + boff + n * 2048 + k * 1024); } while (0)
; #define PG8_MMA(ai, bj, At, Bt) do { __builtin_amdgcn_s_setprio(1); _Pragma("unroll") for (int m = 0; m < 4; ++m) _Pragma("unroll") for (int n = 0; n < 2; ++n) _Pragma("unroll") for (int k = 0; k < 2; ++k) \
;         acc[ai][bj][m][n] = __builtin_amdgcn_mfma_f32_16x16x32_bf16(Bt[n][k], At[m][k], acc[ai][bj][m][n], 0, 0, 0); __builtin_amdgcn_s_setprio(0); } while (0)
; #define PG8_WAIT_V(n) asm volatile("s_waitcnt vmcnt(" #n ")" ::: "memory")
; #define PG8_WAIT_L(n) asm volatile("s_waitcnt lgkmcnt(" #n ")" ::: "memory")
; #define PG8_BAR __builtin_amdgcn_s_barrier()
; #define PG8_SCHED __builtin_amdgcn_sched_barrier(0)
; template <class Epi, class Sched, bool ALIGN_EPI = false, bool SP2 = false>
; __device__ __forceinline__ void gemm_phase(PG8_LAS unsigned char* lds, const Gemm g, const Sched& S, const Epi& E) {
;     ...
;             PG8_WAIT_V(8); PG8_WAIT_L(0); PG8_BAR; PG8_MMA(1, 0, At, B0); PG8_MMA(1, 1, At, B1); PG8_BAR; PG8_SCHED;
;             PG8_LDB(B0, 1, 0); PG8_LDB(B1, 1, 1); PG8_SCHED; PG8_LDA(At, 1, 0); PG8_STAGE(PG8_SA(0, 1), a2 + hstep, voffA);
;             PG8_WAIT_V(8); PG8_WAIT_L(0); PG8_BAR; PG8_MMA(0, 0, At, B0); PG8_MMA(0, 1, At, B1); PG8_BAR; PG8_SCHED;
	v_mfma_f32_16x16x32_bf16 v[62:65], v[144:147], v[188:191], 0
	v_mfma_f32_16x16x32_bf16 v[62:65], v[160:163], v[206:209], v[62:65]
	v_mfma_f32_16x16x32_bf16 v[58:61], v[168:171], v[206:209], 0
	v_mfma_f32_16x16x32_bf16 v[58:61], v[164:167], v[188:191], v[58:61]
	v_mfma_f32_16x16x32_bf16 v[42:45], v[164:167], v[210:213], 0
	v_mfma_f32_16x16x32_bf16 v[42:45], v[168:171], v[214:217], v[42:45]
	v_mfma_f32_16x16x32_bf16 v[46:49], v[160:163], v[214:217], 0
	v_mfma_f32_16x16x32_bf16 v[46:49], v[144:147], v[210:213], v[46:49]
	v_mfma_f32_16x16x32_bf16 v[30:33], v[144:147], v[218:221], 0
	v_mfma_f32_16x16x32_bf16 v[30:33], v[160:163], v[222:225], v[30:33]
	v_mfma_f32_16x16x32_bf16 v[26:29], v[168:171], v[222:225], 0
	v_mfma_f32_16x16x32_bf16 v[26:29], v[164:167], v[218:221], v[26:29]
	v_mfma_f32_16x16x32_bf16 v[10:13], v[164:167], v[226:229], 0
	v_mfma_f32_16x16x32_bf16 v[10:13], v[168:171], v[230:233], v[10:13]
	v_mfma_f32_16x16x32_bf16 v[14:17], v[160:163], v[230:233], 0
	v_mfma_f32_16x16x32_bf16 v[14:17], v[144:147], v[226:229], v[14:17]
	v_mfma_f32_16x16x32_bf16 v[54:57], v[172:175], v[188:191], 0
	v_mfma_f32_16x16x32_bf16 v[54:57], v[176:179], v[206:209], v[54:57]
	v_mfma_f32_16x16x32_bf16 v[50:53], v[184:187], v[206:209], 0
	v_mfma_f32_16x16x32_bf16 v[50:53], v[180:183], v[188:191], v[50:53]
	v_mfma_f32_16x16x32_bf16 v[34:37], v[180:183], v[210:213], 0
	v_mfma_f32_16x16x32_bf16 v[34:37], v[184:187], v[214:217], v[34:37]
	v_mfma_f32_16x16x32_bf16 v[38:41], v[176:179], v[214:217], 0
	v_mfma_f32_16x16x32_bf16 v[38:41], v[172:175], v[210:213], v[38:41]
	v_mfma_f32_16x16x32_bf16 v[22:25], v[172:175], v[218:221], 0
	v_mfma_f32_16x16x32_bf16 v[22:25], v[176:179], v[222:225], v[22:25]
	v_mfma_f32_16x16x32_bf16 v[18:21], v[184:187], v[222:225], 0
	v_mfma_f32_16x16x32_bf16 v[18:21], v[180:183], v[218:221], v[18:21]
	v_mfma_f32_16x16x32_bf16 v[2:5], v[180:183], v[226:229], 0
	v_mfma_f32_16x16x32_bf16 v[2:5], v[184:187], v[230:233], v[2:5]
	v_mfma_f32_16x16x32_bf16 v[6:9], v[176:179], v[230:233], 0
	v_mfma_f32_16x16x32_bf16 v[6:9], v[172:175], v[226:229], v[6:9]
	s_barrier
	s_add_i32 s72, 0, 0x18000
	v_add_u32_e32 v153, s72, v150
	s_add_i32 s73, 0, 0x1c000
	ds_read_b128 v[144:147], v153
	ds_read_b128 v[160:163], v153 offset:1024
	ds_read_b128 v[164:167], v153 offset:2048
	ds_read_b128 v[168:171], v153 offset:3072
	v_add_u32_e32 v153, s73, v150
	ds_read_b128 v[172:175], v153
	ds_read_b128 v[176:179], v153 offset:1024
	ds_read_b128 v[180:183], v153 offset:2048
	ds_read_b128 v[184:187], v153 offset:3072
	s_add_u32 s24, s46, 0x40000
	s_addc_u32 s25, s47, 0
	s_mov_b32 m0, s57
	v_lshl_add_u64 v[236:237], s[24:25], 0, v[130:131]
	ds_read_b128 v[188:191], v152 offset:32768
	ds_read_b128 v[206:209], v152 offset:33792
	ds_read_b128 v[210:213], v152 offset:34816
	ds_read_b128 v[214:217], v152 offset:35840
	ds_read_b128 v[218:221], v152 offset:36864
	ds_read_b128 v[222:225], v152 offset:37888
	ds_read_b128 v[226:229], v152 offset:38912
	ds_read_b128 v[230:233], v152 offset:39936
	global_load_lds_dwordx4 v[236:237], off
	v_lshl_add_u64 v[236:237], s[24:25], 0, v[134:135]
	s_mov_b32 m0, s58
	s_nop 0
	global_load_lds_dwordx4 v[236:237], off
	s_waitcnt vmcnt(8) lgkmcnt(0)
	s_barrier
	v_mfma_f32_16x16x32_bf16 v[126:129], v[144:147], v[188:191], v[126:129]
	v_mfma_f32_16x16x32_bf16 v[126:129], v[160:163], v[206:209], v[126:129]
	v_mfma_f32_16x16x32_bf16 v[122:125], v[168:171], v[206:209], v[122:125]
	v_mfma_f32_16x16x32_bf16 v[122:125], v[164:167], v[188:191], v[122:125]
	v_mfma_f32_16x16x32_bf16 v[106:109], v[164:167], v[210:213], v[106:109]
	v_mfma_f32_16x16x32_bf16 v[106:109], v[168:171], v[214:217], v[106:109]
	v_mfma_f32_16x16x32_bf16 v[110:113], v[160:163], v[214:217], v[110:113]
	v_mfma_f32_16x16x32_bf16 v[110:113], v[144:147], v[210:213], v[110:113]
	v_mfma_f32_16x16x32_bf16 v[94:97], v[144:147], v[218:221], v[94:97]
	v_mfma_f32_16x16x32_bf16 v[94:97], v[160:163], v[222:225], v[94:97]
	v_mfma_f32_16x16x32_bf16 v[90:93], v[168:171], v[222:225], v[90:93]
	v_mfma_f32_16x16x32_bf16 v[90:93], v[164:167], v[218:221], v[90:93]
	v_mfma_f32_16x16x32_bf16 v[74:77], v[164:167], v[226:229], v[74:77]
	v_mfma_f32_16x16x32_bf16 v[74:77], v[168:171], v[230:233], v[74:77]
	v_mfma_f32_16x16x32_bf16 v[78:81], v[160:163], v[230:233], v[78:81]
	v_mfma_f32_16x16x32_bf16 v[78:81], v[144:147], v[226:229], v[78:81]
	v_mfma_f32_16x16x32_bf16 v[118:121], v[172:175], v[188:191], v[118:121]
	v_mfma_f32_16x16x32_bf16 v[118:121], v[176:179], v[206:209], v[118:121]
	v_mfma_f32_16x16x32_bf16 v[114:117], v[184:187], v[206:209], v[114:117]
	v_mfma_f32_16x16x32_bf16 v[114:117], v[180:183], v[188:191], v[114:117]
	v_mfma_f32_16x16x32_bf16 v[98:101], v[180:183], v[210:213], v[98:101]
	v_mfma_f32_16x16x32_bf16 v[98:101], v[184:187], v[214:217], v[98:101]
	v_mfma_f32_16x16x32_bf16 v[102:105], v[176:179], v[214:217], v[102:105]
	v_mfma_f32_16x16x32_bf16 v[102:105], v[172:175], v[210:213], v[102:105]
	v_mfma_f32_16x16x32_bf16 v[86:89], v[172:175], v[218:221], v[86:89]
	v_mfma_f32_16x16x32_bf16 v[86:89], v[176:179], v[222:225], v[86:89]
	v_mfma_f32_16x16x32_bf16 v[82:85], v[184:187], v[222:225], v[82:85]
	v_mfma_f32_16x16x32_bf16 v[82:85], v[180:183], v[218:221], v[82:85]
	v_mfma_f32_16x16x32_bf16 v[66:69], v[180:183], v[226:229], v[66:69]
	v_mfma_f32_16x16x32_bf16 v[66:69], v[184:187], v[230:233], v[66:69]
	v_mfma_f32_16x16x32_bf16 v[70:73], v[176:179], v[230:233], v[70:73]
	v_mfma_f32_16x16x32_bf16 v[70:73], v[172:175], v[226:229], v[70:73]
	s_barrier
; #define PG8_STAGE(bufoff, gbase, voff) do { _Pragma("unroll") for (int _i = 0; _i < 2; ++_i) \
;         __builtin_amdgcn_global_load_lds((const unsigned*)((const char*)(gbase) + (voff)[_i]), (PG8_LAS unsigned*)(lds + (bufoff) + ldsw + _i * 8192), 16, 0, 0); } while (0)
; #define PG8_LDA(dst, b, h) do { _Pragma("unroll") for (int m = 0; m < 4; ++m) _Pragma("unroll") for (int k = 0; k < 2; ++k) dst[m][k] = *(const PG8_LAS bf16x8*)(lds + PG8_SA(b, h) + aoff + m * 2048 + k * 1024); } while (0)
; #define PG8_LDB(dst, b, h) do { _Pragma("unroll") for (int n = 0; n < 2; ++n) _Pragma("unroll") for (int k = 0; k < 2; ++k) dst[n][k] = *(const PG8_LAS bf16x8*)(lds + PG8_SB(b, h) + boff + n * 2048 + k * 1024); } while (0)
; #define PG8_MMA(ai, bj, At, Bt) do { __builtin_amdgcn_s_setprio(1); _Pragma("unroll") for (int m = 0; m < 4; ++m) _Pragma("unroll") for (int n = 0; n < 2; ++n) _Pragma("unroll") for (int k = 0; k < 2; ++k) \
;         acc[ai][bj][m][n] = __builtin_amdgcn_mfma_f32_16x16x32_bf16(Bt[n][k], At[m][k], acc[ai][bj][m][n], 0, 0, 0); __builtin_amdgcn_s_setprio(0); } while (0)
; #define PG8_WAIT_V(n) asm volatile("s_waitcnt vmcnt(" #n ")" ::: "memory")
; #define PG8_BAR __builtin_amdgcn_s_barrier()
; template <class Epi, class Sched, bool ALIGN_EPI = false, bool SP2 = false>
; __device__ __forceinline__ void gemm_phase(PG8_LAS unsigned char* lds, const Gemm g, const Sched& S, const Epi& E) {
;     ...
;         for (int t = 0; t < nt; t += 2) {
;             const bool last = (t == nt - 2);
;             const char* a1 = cA + (size_t)(t + 1) * kstepA;
;             const char* a2 = last ? nA : cA + (size_t)(t + 2) * kstepA; const char* b2 = last ? nB : cB + (size_t)(t + 2) * kstep;
;             const char* a3 = a2 + kstepA; const char* b3 = b2 + kstep;
;             if (last && has_next) S.a_ready(nxt);
;             if constexpr (SP2) {
;             PG8_LDB(B0, 0, 0); PG8_LDB(B1, 0, 1); PG8_SCHED; PG8_LDA(At, 0, 0); PG8_STAGE(PG8_SA(1, 1), a1 + hstep, voffA);
;             PG8_WAIT_V(8); PG8_WAIT_L(0); PG8_BAR; PG8_MMA(0, 0, At, B0); PG8_MMA(0, 1, At, B1); PG8_BAR; PG8_SCHED;
;     ...
;             PG8_LDA(At, 1, 1); PG8_STAGE(PG8_SB(1, 0), b3, voffB); PG8_STAGE(PG8_SB(1, 1), b3 + hstep, voffB); PG8_STAGE(PG8_SA(1, 0), a3, voffA);
;             PG8_WAIT_V(8); PG8_WAIT_L(0); PG8_BAR; PG8_MMA(1, 0, At, B0); PG8_MMA(1, 1, At, B1); PG8_BAR; PG8_SCHED;
	s_add_i32 s24, s72, s51
	v_lshl_add_u64 v[148:149], v[148:149], 0, s[38:39]
	s_mov_b32 m0, s24
	ds_read_b128 v[188:191], v152 offset:49152
	ds_read_b128 v[206:209], v152 offset:50176
	ds_read_b128 v[210:213], v152 offset:51200
	ds_read_b128 v[214:217], v152 offset:52224
	ds_read_b128 v[218:221], v152 offset:53248
	ds_read_b128 v[222:225], v152 offset:54272
	ds_read_b128 v[226:229], v152 offset:55296
	ds_read_b128 v[230:233], v152 offset:56320
	global_load_lds_dwordx4 v[148:149], off
	s_add_i32 m0, s24, 0x2000
	s_add_u32 s24, s42, 0x40080
	v_lshl_add_u64 v[148:149], v[234:235], 0, s[38:39]
	s_addc_u32 s25, s43, 0
	s_add_i32 s42, s73, s51
	global_load_lds_dwordx4 v[148:149], off
	v_lshl_add_u64 v[148:149], s[24:25], 0, v[132:133]
	s_mov_b32 m0, s42
	s_nop 0
	global_load_lds_dwordx4 v[148:149], off
	v_lshl_add_u64 v[148:149], s[24:25], 0, v[136:137]
	s_add_i32 m0, s42, 0x2000
	s_nop 0
	global_load_lds_dwordx4 v[148:149], off
	v_lshl_add_u64 v[148:149], s[26:27], 0, v[130:131]
	s_mov_b32 m0, s64
	s_nop 0
	global_load_lds_dwordx4 v[148:149], off
	v_lshl_add_u64 v[148:149], s[26:27], 0, v[134:135]
	s_mov_b32 m0, s65
	s_nop 0
	global_load_lds_dwordx4 v[148:149], off
	s_waitcnt vmcnt(8) lgkmcnt(0)
	s_barrier
	v_mfma_f32_16x16x32_bf16 v[62:65], v[144:147], v[188:191], v[62:65]
	v_mfma_f32_16x16x32_bf16 v[62:65], v[160:163], v[206:209], v[62:65]
	v_mfma_f32_16x16x32_bf16 v[58:61], v[168:171], v[206:209], v[58:61]
	v_mfma_f32_16x16x32_bf16 v[58:61], v[164:167], v[188:191], v[58:61]
	v_mfma_f32_16x16x32_bf16 v[42:45], v[164:167], v[210:213], v[42:45]
	v_mfma_f32_16x16x32_bf16 v[42:45], v[168:171], v[214:217], v[42:45]
	v_mfma_f32_16x16x32_bf16 v[46:49], v[160:163], v[214:217], v[46:49]
	v_mfma_f32_16x16x32_bf16 v[46:49], v[144:147], v[210:213], v[46:49]
	v_mfma_f32_16x16x32_bf16 v[30:33], v[144:147], v[218:221], v[30:33]
	v_mfma_f32_16x16x32_bf16 v[30:33], v[160:163], v[222:225], v[30:33]
	v_mfma_f32_16x16x32_bf16 v[26:29], v[168:171], v[222:225], v[26:29]
	v_mfma_f32_16x16x32_bf16 v[26:29], v[164:167], v[218:221], v[26:29]
	v_mfma_f32_16x16x32_bf16 v[10:13], v[164:167], v[226:229], v[10:13]
	v_mfma_f32_16x16x32_bf16 v[10:13], v[168:171], v[230:233], v[10:13]
	v_mfma_f32_16x16x32_bf16 v[14:17], v[160:163], v[230:233], v[14:17]
	v_mfma_f32_16x16x32_bf16 v[14:17], v[144:147], v[226:229], v[14:17]
	v_mfma_f32_16x16x32_bf16 v[54:57], v[172:175], v[188:191], v[54:57]
	v_mfma_f32_16x16x32_bf16 v[54:57], v[176:179], v[206:209], v[54:57]
	v_mfma_f32_16x16x32_bf16 v[50:53], v[184:187], v[206:209], v[50:53]
	v_mfma_f32_16x16x32_bf16 v[50:53], v[180:183], v[188:191], v[50:53]
	v_mfma_f32_16x16x32_bf16 v[34:37], v[180:183], v[210:213], v[34:37]
	v_mfma_f32_16x16x32_bf16 v[34:37], v[184:187], v[214:217], v[34:37]
	v_mfma_f32_16x16x32_bf16 v[38:41], v[176:179], v[214:217], v[38:41]
	v_mfma_f32_16x16x32_bf16 v[38:41], v[172:175], v[210:213], v[38:41]
	v_mfma_f32_16x16x32_bf16 v[22:25], v[172:175], v[218:221], v[22:25]
	v_mfma_f32_16x16x32_bf16 v[22:25], v[176:179], v[222:225], v[22:25]
	v_mfma_f32_16x16x32_bf16 v[18:21], v[184:187], v[222:225], v[18:21]
	v_mfma_f32_16x16x32_bf16 v[18:21], v[180:183], v[218:221], v[18:21]
	v_mfma_f32_16x16x32_bf16 v[2:5], v[180:183], v[226:229], v[2:5]
	v_mfma_f32_16x16x32_bf16 v[2:5], v[184:187], v[230:233], v[2:5]
	v_mfma_f32_16x16x32_bf16 v[6:9], v[176:179], v[230:233], v[6:9]
	v_mfma_f32_16x16x32_bf16 v[6:9], v[172:175], v[226:229], v[6:9]
	s_barrier
	s_add_i32 s71, s71, 2
	s_add_u32 s69, s69, 0x100
	s_addc_u32 s70, s70, 0
	s_cmp_gt_u32 s71, 13
	s_mov_b64 s[24:25], s[2:3]
	s_cbranch_scc1 .Lpeel_exit_0
.LBB0_238:
	s_add_u32 s2, s24, 0x8000
	s_addc_u32 s3, s25, 0
	s_cmp_eq_u32 s71, 12
	s_cselect_b32 s46, s67, s2
	s_cselect_b32 s47, s11, s3
	s_cselect_b32 s42, s68, s69
	s_cselect_b32 s43, s9, s70
	s_add_u32 s26, s46, 0x4000
	s_addc_u32 s27, s47, 0
	v_add_u32_e32 v148, s76, v150
	s_add_i32 s72, 0, 0x14000
	ds_read_b128 v[144:147], v148
	ds_read_b128 v[160:163], v148 offset:1024
	ds_read_b128 v[164:167], v148 offset:2048
	ds_read_b128 v[168:171], v148 offset:3072
	v_add_u32_e32 v148, s72, v150
	ds_read_b128 v[172:175], v148
	ds_read_b128 v[176:179], v148 offset:1024
	ds_read_b128 v[180:183], v148 offset:2048
	ds_read_b128 v[184:187], v148 offset:3072
	v_lshl_add_u64 v[148:149], s[24:25], 0, v[142:143]
	s_add_i32 m0, s23, 0xc000
	ds_read_b128 v[188:191], v152
	ds_read_b128 v[206:209], v152 offset:1024
	ds_read_b128 v[210:213], v152 offset:2048
	ds_read_b128 v[214:217], v152 offset:3072
	ds_read_b128 v[218:221], v152 offset:4096
	ds_read_b128 v[222:225], v152 offset:5120
	ds_read_b128 v[226:229], v152 offset:6144
	ds_read_b128 v[230:233], v152 offset:7168
	global_load_lds_dwordx4 v[148:149], off
	v_lshl_add_u64 v[148:149], s[24:25], 0, v[140:141]
	s_add_i32 m0, s23, 0xe000
	s_nop 0
	global_load_lds_dwordx4 v[148:149], off
	s_waitcnt vmcnt(8) lgkmcnt(0)
	s_barrier
; #define PG8_STAGE(bufoff, gbase, voff) do { _Pragma("unroll") for (int _i = 0; _i < 2; ++_i) \
;         __builtin_amdgcn_global_load_lds((const unsigned*)((const char*)(gbase) + (voff)[_i]), (PG8_LAS unsigned*)(lds + (bufoff) + ldsw + _i * 8192), 16, 0, 0); } while (0)
; #define PG8_LDA(dst, b, h) do { _Pragma("unroll") for (int m = 0; m < 4; ++m) _Pragma("unroll") for (int k = 0; k < 2; ++k) dst[m][k] = *(const PG8_LAS bf16x8*)(lds + PG8_SA(b, h) + aoff + m * 2048 + k * 1024); } while (0)
; #define PG8_MMA(ai, bj, At, Bt) do { __builtin_amdgcn_s_setprio(1); _Pragma("unroll") for (int m = 0; m < 4; ++m) _Pragma("unroll") for (int n = 0; n < 2; ++n) _Pragma("unroll") for (int k = 0; k < 2; ++k) \
;         acc[ai][bj][m][n] = __builtin_amdgcn_mfma_f32_16x16x32_bf16(Bt[n][k], At[m][k], acc[ai][bj][m][n], 0, 0, 0); __builtin_amdgcn_s_setprio(0); } while (0)
; #define PG8_WAIT_V(n) asm volatile("s_waitcnt vmcnt(" #n ")" ::: "memory")
; #define PG8_WAIT_L(n) asm volatile("s_waitcnt lgkmcnt(" #n ")" ::: "memory")
; #define PG8_BAR __builtin_amdgcn_s_barrier()
; #define PG8_SCHED __builtin_amdgcn_sched_barrier(0)
; template <class Epi, class Sched, bool ALIGN_EPI = false, bool SP2 = false>
; __device__ __forceinline__ void gemm_phase(PG8_LAS unsigned char* lds, const Gemm g, const Sched& S, const Epi& E) {
;     ...
;             PG8_WAIT_V(8); PG8_WAIT_L(0); PG8_BAR; PG8_MMA(0, 0, At, B0); PG8_MMA(0, 1, At, B1); PG8_BAR; PG8_SCHED;
;             PG8_LDA(At, 0, 1); PG8_STAGE(PG8_SB(0, 0), b2, voffB); PG8_STAGE(PG8_SB(0, 1), b2 + hstep, voffB); PG8_STAGE(PG8_SA(0, 0), a2, voffA);
;             PG8_WAIT_V(8); PG8_WAIT_L(0); PG8_BAR; PG8_MMA(1, 0, At, B0); PG8_MMA(1, 1, At, B1); PG8_BAR; PG8_SCHED;
	v_mfma_f32_16x16x32_bf16 v[126:129], v[144:147], v[188:191], v[126:129]
	v_mfma_f32_16x16x32_bf16 v[126:129], v[160:163], v[206:209], v[126:129]
	v_mfma_f32_16x16x32_bf16 v[122:125], v[168:171], v[206:209], v[122:125]
	v_mfma_f32_16x16x32_bf16 v[122:125], v[164:167], v[188:191], v[122:125]
	v_mfma_f32_16x16x32_bf16 v[106:109], v[164:167], v[210:213], v[106:109]
	v_mfma_f32_16x16x32_bf16 v[106:109], v[168:171], v[214:217], v[106:109]
	v_mfma_f32_16x16x32_bf16 v[110:113], v[160:163], v[214:217], v[110:113]
	v_mfma_f32_16x16x32_bf16 v[110:113], v[144:147], v[210:213], v[110:113]
	v_mfma_f32_16x16x32_bf16 v[94:97], v[144:147], v[218:221], v[94:97]
	v_mfma_f32_16x16x32_bf16 v[94:97], v[160:163], v[222:225], v[94:97]
	v_mfma_f32_16x16x32_bf16 v[90:93], v[168:171], v[222:225], v[90:93]
	v_mfma_f32_16x16x32_bf16 v[90:93], v[164:167], v[218:221], v[90:93]
	v_mfma_f32_16x16x32_bf16 v[74:77], v[164:167], v[226:229], v[74:77]
	v_mfma_f32_16x16x32_bf16 v[74:77], v[168:171], v[230:233], v[74:77]
	v_mfma_f32_16x16x32_bf16 v[78:81], v[160:163], v[230:233], v[78:81]
	v_mfma_f32_16x16x32_bf16 v[78:81], v[144:147], v[226:229], v[78:81]
	v_mfma_f32_16x16x32_bf16 v[118:121], v[172:175], v[188:191], v[118:121]
	v_mfma_f32_16x16x32_bf16 v[118:121], v[176:179], v[206:209], v[118:121]
	v_mfma_f32_16x16x32_bf16 v[114:117], v[184:187], v[206:209], v[114:117]
	v_mfma_f32_16x16x32_bf16 v[114:117], v[180:183], v[188:191], v[114:117]
	v_mfma_f32_16x16x32_bf16 v[98:101], v[180:183], v[210:213], v[98:101]
	v_mfma_f32_16x16x32_bf16 v[98:101], v[184:187], v[214:217], v[98:101]
	v_mfma_f32_16x16x32_bf16 v[102:105], v[176:179], v[214:217], v[102:105]
	v_mfma_f32_16x16x32_bf16 v[102:105], v[172:175], v[210:213], v[102:105]
	v_mfma_f32_16x16x32_bf16 v[86:89], v[172:175], v[218:221], v[86:89]
	v_mfma_f32_16x16x32_bf16 v[86:89], v[176:179], v[222:225], v[86:89]
	v_mfma_f32_16x16x32_bf16 v[82:85], v[184:187], v[222:225], v[82:85]
	v_mfma_f32_16x16x32_bf16 v[82:85], v[180:183], v[218:221], v[82:85]
	v_mfma_f32_16x16x32_bf16 v[66:69], v[180:183], v[226:229], v[66:69]
	v_mfma_f32_16x16x32_bf16 v[66:69], v[184:187], v[230:233], v[66:69]
	v_mfma_f32_16x16x32_bf16 v[70:73], v[176:179], v[230:233], v[70:73]
	v_mfma_f32_16x16x32_bf16 v[70:73], v[172:175], v[226:229], v[70:73]
	s_barrier
	s_add_i32 s24, s76, s51
	v_lshl_add_u64 v[148:149], s[42:43], 0, v[132:133]
	s_mov_b32 m0, s24
	ds_read_b128 v[188:191], v152 offset:16384
	ds_read_b128 v[206:209], v152 offset:17408
	ds_read_b128 v[210:213], v152 offset:18432
	ds_read_b128 v[214:217], v152 offset:19456
	ds_read_b128 v[218:221], v152 offset:20480
	ds_read_b128 v[222:225], v152 offset:21504
	ds_read_b128 v[226:229], v152 offset:22528
	ds_read_b128 v[230:233], v152 offset:23552
	global_load_lds_dwordx4 v[148:149], off
	s_add_i32 m0, s24, 0x2000
	s_add_u32 s24, s42, 0x40000
	v_lshl_add_u64 v[234:235], s[42:43], 0, v[136:137]
	s_addc_u32 s25, s43, 0
	s_add_i32 s72, s72, s51
	global_load_lds_dwordx4 v[234:235], off
	v_lshl_add_u64 v[236:237], s[24:25], 0, v[132:133]
	s_mov_b32 m0, s72
	s_nop 0
	global_load_lds_dwordx4 v[236:237], off
	v_lshl_add_u64 v[236:237], s[24:25], 0, v[136:137]
	s_add_i32 m0, s72, 0x2000
	s_nop 0
	global_load_lds_dwordx4 v[236:237], off
	v_lshl_add_u64 v[236:237], s[46:47], 0, v[130:131]
	s_mov_b32 m0, s23
	s_nop 0
	global_load_lds_dwordx4 v[236:237], off
	v_lshl_add_u64 v[236:237], s[46:47], 0, v[134:135]
	s_mov_b32 m0, s56
	s_nop 0
	global_load_lds_dwordx4 v[236:237], off
	s_waitcnt vmcnt(8) lgkmcnt(0)
	s_barrier
	v_mfma_f32_16x16x32_bf16 v[62:65], v[144:147], v[188:191], v[62:65]
	v_mfma_f32_16x16x32_bf16 v[62:65], v[160:163], v[206:209], v[62:65]
	v_mfma_f32_16x16x32_bf16 v[58:61], v[168:171], v[206:209], v[58:61]
	v_mfma_f32_16x16x32_bf16 v[58:61], v[164:167], v[188:191], v[58:61]
	v_mfma_f32_16x16x32_bf16 v[42:45], v[164:167], v[210:213], v[42:45]
	v_mfma_f32_16x16x32_bf16 v[42:45], v[168:171], v[214:217], v[42:45]
	v_mfma_f32_16x16x32_bf16 v[46:49], v[160:163], v[214:217], v[46:49]
	v_mfma_f32_16x16x32_bf16 v[46:49], v[144:147], v[210:213], v[46:49]
	v_mfma_f32_16x16x32_bf16 v[30:33], v[144:147], v[218:221], v[30:33]
	v_mfma_f32_16x16x32_bf16 v[30:33], v[160:163], v[222:225], v[30:33]
	v_mfma_f32_16x16x32_bf16 v[26:29], v[168:171], v[222:225], v[26:29]
	v_mfma_f32_16x16x32_bf16 v[26:29], v[164:167], v[218:221], v[26:29]
	v_mfma_f32_16x16x32_bf16 v[10:13], v[164:167], v[226:229], v[10:13]
	v_mfma_f32_16x16x32_bf16 v[10:13], v[168:171], v[230:233], v[10:13]
	v_mfma_f32_16x16x32_bf16 v[14:17], v[160:163], v[230:233], v[14:17]
	v_mfma_f32_16x16x32_bf16 v[14:17], v[144:147], v[226:229], v[14:17]
	v_mfma_f32_16x16x32_bf16 v[54:57], v[172:175], v[188:191], v[54:57]
	v_mfma_f32_16x16x32_bf16 v[54:57], v[176:179], v[206:209], v[54:57]
	v_mfma_f32_16x16x32_bf16 v[50:53], v[184:187], v[206:209], v[50:53]
	v_mfma_f32_16x16x32_bf16 v[50:53], v[180:183], v[188:191], v[50:53]
	v_mfma_f32_16x16x32_bf16 v[34:37], v[180:183], v[210:213], v[34:37]
	v_mfma_f32_16x16x32_bf16 v[34:37], v[184:187], v[214:217], v[34:37]
	v_mfma_f32_16x16x32_bf16 v[38:41], v[176:179], v[214:217], v[38:41]
	v_mfma_f32_16x16x32_bf16 v[38:41], v[172:175], v[210:213], v[38:41]
	v_mfma_f32_16x16x32_bf16 v[22:25], v[172:175], v[218:221], v[22:25]
	v_mfma_f32_16x16x32_bf16 v[22:25], v[176:179], v[222:225], v[22:25]
	v_mfma_f32_16x16x32_bf16 v[18:21], v[184:187], v[222:225], v[18:21]
	v_mfma_f32_16x16x32_bf16 v[18:21], v[180:183], v[218:221], v[18:21]
	v_mfma_f32_16x16x32_bf16 v[2:5], v[180:183], v[226:229], v[2:5]
	v_mfma_f32_16x16x32_bf16 v[2:5], v[184:187], v[230:233], v[2:5]
	v_mfma_f32_16x16x32_bf16 v[6:9], v[176:179], v[230:233], v[6:9]
	v_mfma_f32_16x16x32_bf16 v[6:9], v[172:175], v[226:229], v[6:9]
	s_barrier
; #define PG8_STAGE(bufoff, gbase, voff) do { _Pragma("unroll") for (int _i = 0; _i < 2; ++_i) \
;         __builtin_amdgcn_global_load_lds((const unsigned*)((const char*)(gbase) + (voff)[_i]), (PG8_LAS unsigned*)(lds + (bufoff) + ldsw + _i * 8192), 16, 0, 0); } while (0)
; #define PG8_LDA(dst, b, h) do { _Pragma("unroll") for (int m = 0; m < 4; ++m) _Pragma("unroll") for (int k = 0; k < 2; ++k) dst[m][k] = *(const PG8_LAS bf16x8*)(lds + PG8_SA(b, h) + aoff + m * 2048 + k * 1024); } while (0)
; #define PG8_LDB(dst, b, h) do { _Pragma("unroll") for (int n = 0; n < 2; ++n) _Pragma("unroll") for (int k = 0; k < 2; ++k) dst[n][k] = *(const PG8_LAS bf16x8*)(lds + PG8_SB(b, h) + boff + n * 2048 + k * 1024); } while (0)
; #define PG8_MMA(ai, bj, At, Bt) do { __builtin_amdgcn_s_setprio(1); _Pragma("unroll") for (int m = 0; m < 4; ++m) _Pragma("unroll") for (int n = 0; n < 2; ++n) _Pragma("unroll") for (int k = 0; k < 2; ++k) \
;         acc[ai][bj][m][n] = __builtin_amdgcn_mfma_f32_16x16x32_bf16(Bt[n][k], At[m][k], acc[ai][bj][m][n], 0, 0, 0); __builtin_amdgcn_s_setprio(0); } while (0)
; #define PG8_WAIT_V(n) asm volatile("s_waitcnt vmcnt(" #n ")" ::: "memory")
; #define PG8_WAIT_L(n) asm volatile("s_waitcnt lgkmcnt(" #n ")" ::: "memory")
; #define PG8_BAR __builtin_amdgcn_s_barrier()
; #define PG8_SCHED __builtin_amdgcn_sched_barrier(0)
; template <class Epi, class Sched, bool ALIGN_EPI = false, bool SP2 = false>
; __device__ __forceinline__ void gemm_phase(PG8_LAS unsigned char* lds, const Gemm g, const Sched& S, const Epi& E) {
;     ...
;             PG8_LDB(B0, 1, 0); PG8_LDB(B1, 1, 1); PG8_SCHED; PG8_LDA(At, 1, 0); PG8_STAGE(PG8_SA(0, 1), a2 + hstep, voffA);
;             PG8_WAIT_V(8); PG8_WAIT_L(0); PG8_BAR; PG8_MMA(0, 0, At, B0); PG8_MMA(0, 1, At, B1); PG8_BAR; PG8_SCHED;
;             PG8_LDA(At, 1, 1); PG8_STAGE(PG8_SB(1, 0), b3, voffB); PG8_STAGE(PG8_SB(1, 1), b3 + hstep, voffB); PG8_STAGE(PG8_SA(1, 0), a3, voffA);
;             PG8_WAIT_V(8); PG8_WAIT_L(0); PG8_BAR; PG8_MMA(1, 0, At, B0); PG8_MMA(1, 1, At, B1); PG8_BAR; PG8_SCHED;
	s_add_i32 s72, 0, 0x18000
	v_add_u32_e32 v153, s72, v150
	s_add_i32 s73, 0, 0x1c000
	ds_read_b128 v[144:147], v153
	ds_read_b128 v[160:163], v153 offset:1024
	ds_read_b128 v[164:167], v153 offset:2048
	ds_read_b128 v[168:171], v153 offset:3072
	v_add_u32_e32 v153, s73, v150
	ds_read_b128 v[172:175], v153
	ds_read_b128 v[176:179], v153 offset:1024
	ds_read_b128 v[180:183], v153 offset:2048
	ds_read_b128 v[184:187], v153 offset:3072
	s_add_u32 s24, s46, 0x40000
	s_addc_u32 s25, s47, 0
	s_mov_b32 m0, s57
	v_lshl_add_u64 v[236:237], s[24:25], 0, v[130:131]
	ds_read_b128 v[188:191], v152 offset:32768
	ds_read_b128 v[206:209], v152 offset:33792
	ds_read_b128 v[210:213], v152 offset:34816
	ds_read_b128 v[214:217], v152 offset:35840
	ds_read_b128 v[218:221], v152 offset:36864
	ds_read_b128 v[222:225], v152 offset:37888
	ds_read_b128 v[226:229], v152 offset:38912
	ds_read_b128 v[230:233], v152 offset:39936
	global_load_lds_dwordx4 v[236:237], off
	v_lshl_add_u64 v[236:237], s[24:25], 0, v[134:135]
	s_mov_b32 m0, s58
	s_nop 0
	global_load_lds_dwordx4 v[236:237], off
	s_waitcnt vmcnt(8) lgkmcnt(0)
	s_barrier
	v_mfma_f32_16x16x32_bf16 v[126:129], v[144:147], v[188:191], v[126:129]
	v_mfma_f32_16x16x32_bf16 v[126:129], v[160:163], v[206:209], v[126:129]
	v_mfma_f32_16x16x32_bf16 v[122:125], v[168:171], v[206:209], v[122:125]
	v_mfma_f32_16x16x32_bf16 v[122:125], v[164:167], v[188:191], v[122:125]
	v_mfma_f32_16x16x32_bf16 v[106:109], v[164:167], v[210:213], v[106:109]
	v_mfma_f32_16x16x32_bf16 v[106:109], v[168:171], v[214:217], v[106:109]
	v_mfma_f32_16x16x32_bf16 v[110:113], v[160:163], v[214:217], v[110:113]
	v_mfma_f32_16x16x32_bf16 v[110:113], v[144:147], v[210:213], v[110:113]
	v_mfma_f32_16x16x32_bf16 v[94:97], v[144:147], v[218:221], v[94:97]
	v_mfma_f32_16x16x32_bf16 v[94:97], v[160:163], v[222:225], v[94:97]
	v_mfma_f32_16x16x32_bf16 v[90:93], v[168:171], v[222:225], v[90:93]
	v_mfma_f32_16x16x32_bf16 v[90:93], v[164:167], v[218:221], v[90:93]
	v_mfma_f32_16x16x32_bf16 v[74:77], v[164:167], v[226:229], v[74:77]
	v_mfma_f32_16x16x32_bf16 v[74:77], v[168:171], v[230:233], v[74:77]
	v_mfma_f32_16x16x32_bf16 v[78:81], v[160:163], v[230:233], v[78:81]
	v_mfma_f32_16x16x32_bf16 v[78:81], v[144:147], v[226:229], v[78:81]
	v_mfma_f32_16x16x32_bf16 v[118:121], v[172:175], v[188:191], v[118:121]
	v_mfma_f32_16x16x32_bf16 v[118:121], v[176:179], v[206:209], v[118:121]
	v_mfma_f32_16x16x32_bf16 v[114:117], v[184:187], v[206:209], v[114:117]
	v_mfma_f32_16x16x32_bf16 v[114:117], v[180:183], v[188:191], v[114:117]
	v_mfma_f32_16x16x32_bf16 v[98:101], v[180:183], v[210:213], v[98:101]
	v_mfma_f32_16x16x32_bf16 v[98:101], v[184:187], v[214:217], v[98:101]
	v_mfma_f32_16x16x32_bf16 v[102:105], v[176:179], v[214:217], v[102:105]
	v_mfma_f32_16x16x32_bf16 v[102:105], v[172:175], v[210:213], v[102:105]
	v_mfma_f32_16x16x32_bf16 v[86:89], v[172:175], v[218:221], v[86:89]
	v_mfma_f32_16x16x32_bf16 v[86:89], v[176:179], v[222:225], v[86:89]
	v_mfma_f32_16x16x32_bf16 v[82:85], v[184:187], v[222:225], v[82:85]
	v_mfma_f32_16x16x32_bf16 v[82:85], v[180:183], v[218:221], v[82:85]
	v_mfma_f32_16x16x32_bf16 v[66:69], v[180:183], v[226:229], v[66:69]
	v_mfma_f32_16x16x32_bf16 v[66:69], v[184:187], v[230:233], v[66:69]
	v_mfma_f32_16x16x32_bf16 v[70:73], v[176:179], v[230:233], v[70:73]
	v_mfma_f32_16x16x32_bf16 v[70:73], v[172:175], v[226:229], v[70:73]
	s_barrier
	s_add_i32 s24, s72, s51
	v_lshl_add_u64 v[148:149], v[148:149], 0, s[38:39]
	s_mov_b32 m0, s24
	ds_read_b128 v[188:191], v152 offset:49152
	ds_read_b128 v[206:209], v152 offset:50176
	ds_read_b128 v[210:213], v152 offset:51200
	ds_read_b128 v[214:217], v152 offset:52224
	ds_read_b128 v[218:221], v152 offset:53248
	ds_read_b128 v[222:225], v152 offset:54272
	ds_read_b128 v[226:229], v152 offset:55296
	ds_read_b128 v[230:233], v152 offset:56320
	global_load_lds_dwordx4 v[148:149], off
	s_add_i32 m0, s24, 0x2000
	s_add_u32 s24, s42, 0x40080
	v_lshl_add_u64 v[148:149], v[234:235], 0, s[38:39]
	s_addc_u32 s25, s43, 0
	s_add_i32 s42, s73, s51
	global_load_lds_dwordx4 v[148:149], off
	v_lshl_add_u64 v[148:149], s[24:25], 0, v[132:133]
	s_mov_b32 m0, s42
	s_nop 0
	global_load_lds_dwordx4 v[148:149], off
	v_lshl_add_u64 v[148:149], s[24:25], 0, v[136:137]
	s_add_i32 m0, s42, 0x2000
	s_nop 0
	global_load_lds_dwordx4 v[148:149], off
	v_lshl_add_u64 v[148:149], s[26:27], 0, v[130:131]
	s_mov_b32 m0, s64
	s_nop 0
	global_load_lds_dwordx4 v[148:149], off
	v_lshl_add_u64 v[148:149], s[26:27], 0, v[134:135]
	s_mov_b32 m0, s65
	s_nop 0
	global_load_lds_dwordx4 v[148:149], off
	s_waitcnt vmcnt(8) lgkmcnt(0)
	s_barrier
	v_mfma_f32_16x16x32_bf16 v[62:65], v[144:147], v[188:191], v[62:65]
	v_mfma_f32_16x16x32_bf16 v[62:65], v[160:163], v[206:209], v[62:65]
	v_mfma_f32_16x16x32_bf16 v[58:61], v[168:171], v[206:209], v[58:61]
	v_mfma_f32_16x16x32_bf16 v[58:61], v[164:167], v[188:191], v[58:61]
	v_mfma_f32_16x16x32_bf16 v[42:45], v[164:167], v[210:213], v[42:45]
	v_mfma_f32_16x16x32_bf16 v[42:45], v[168:171], v[214:217], v[42:45]
	v_mfma_f32_16x16x32_bf16 v[46:49], v[160:163], v[214:217], v[46:49]
	v_mfma_f32_16x16x32_bf16 v[46:49], v[144:147], v[210:213], v[46:49]
	v_mfma_f32_16x16x32_bf16 v[30:33], v[144:147], v[218:221], v[30:33]
	v_mfma_f32_16x16x32_bf16 v[30:33], v[160:163], v[222:225], v[30:33]
	v_mfma_f32_16x16x32_bf16 v[26:29], v[168:171], v[222:225], v[26:29]
	v_mfma_f32_16x16x32_bf16 v[26:29], v[164:167], v[218:221], v[26:29]
	v_mfma_f32_16x16x32_bf16 v[10:13], v[164:167], v[226:229], v[10:13]
	v_mfma_f32_16x16x32_bf16 v[10:13], v[168:171], v[230:233], v[10:13]
	v_mfma_f32_16x16x32_bf16 v[14:17], v[160:163], v[230:233], v[14:17]
	v_mfma_f32_16x16x32_bf16 v[14:17], v[144:147], v[226:229], v[14:17]
	v_mfma_f32_16x16x32_bf16 v[54:57], v[172:175], v[188:191], v[54:57]
	v_mfma_f32_16x16x32_bf16 v[54:57], v[176:179], v[206:209], v[54:57]
	v_mfma_f32_16x16x32_bf16 v[50:53], v[184:187], v[206:209], v[50:53]
	v_mfma_f32_16x16x32_bf16 v[50:53], v[180:183], v[188:191], v[50:53]
	v_mfma_f32_16x16x32_bf16 v[34:37], v[180:183], v[210:213], v[34:37]
	v_mfma_f32_16x16x32_bf16 v[34:37], v[184:187], v[214:217], v[34:37]
	v_mfma_f32_16x16x32_bf16 v[38:41], v[176:179], v[214:217], v[38:41]
	v_mfma_f32_16x16x32_bf16 v[38:41], v[172:175], v[210:213], v[38:41]
	v_mfma_f32_16x16x32_bf16 v[22:25], v[172:175], v[218:221], v[22:25]
	v_mfma_f32_16x16x32_bf16 v[22:25], v[176:179], v[222:225], v[22:25]
	v_mfma_f32_16x16x32_bf16 v[18:21], v[184:187], v[222:225], v[18:21]
	v_mfma_f32_16x16x32_bf16 v[18:21], v[180:183], v[218:221], v[18:21]
	v_mfma_f32_16x16x32_bf16 v[2:5], v[180:183], v[226:229], v[2:5]
	v_mfma_f32_16x16x32_bf16 v[2:5], v[184:187], v[230:233], v[2:5]
	v_mfma_f32_16x16x32_bf16 v[6:9], v[176:179], v[230:233], v[6:9]
	v_mfma_f32_16x16x32_bf16 v[6:9], v[172:175], v[226:229], v[6:9]
	s_barrier
	s_add_i32 s71, s71, 2
	s_add_u32 s69, s69, 0x100
	s_addc_u32 s70, s70, 0
	s_cmp_gt_u32 s71, 13
	s_mov_b64 s[24:25], s[2:3]
	s_cbranch_scc0 .LBB0_238

; #define PG8_STAGE(bufoff, gbase, voff) do { _Pragma("unroll") for (int _i = 0; _i < 2; ++_i) \
;         __builtin_amdgcn_global_load_lds((const unsigned*)((const char*)(gbase) + (voff)[_i]), (PG8_LAS unsigned*)(lds + (bufoff) + ldsw + _i * 8192), 16, 0, 0); } while (0)
; #define PG8_LDA(dst, b, h) do { _Pragma("unroll") for (int m = 0; m < 4; ++m) _Pragma("unroll") for (int k = 0; k < 2; ++k) dst[m][k] = *(const PG8_LAS bf16x8*)(lds + PG8_SA(b, h) + aoff + m * 2048 + k * 1024); } while (0)
; #define PG8_LDB(dst, b, h) do { _Pragma("unroll") for (int n = 0; n < 2; ++n) _Pragma("unroll") for (int k = 0; k < 2; ++k) dst[n][k] = *(const PG8_LAS bf16x8*)(lds + PG8_SB(b, h) + boff + n * 2048 + k * 1024); } while (0)
; #define PG8_WAIT_V(n) asm volatile("s_waitcnt vmcnt(" #n ")" ::: "memory")
; #define PG8_WAIT_L(n) asm volatile("s_waitcnt lgkmcnt(" #n ")" ::: "memory")
; #define PG8_BAR __builtin_amdgcn_s_barrier()
; #define PG8_SCHED __builtin_amdgcn_sched_barrier(0)
; template <class Epi, class Sched, bool ALIGN_EPI = false, bool SP2 = false>
; __device__ __forceinline__ void gemm_phase(PG8_LAS unsigned char* lds, const Gemm g, const Sched& S, const Epi& E) {
;     ...
;         const char* nA = has_next ? (const char*)g.A + (size_t)nxt.pm * tstep : cA; const char* nB = has_next ? (const char*)g.Bt + (size_t)nxt.pn * tstep : cB;
;         for (int t = 0; t < nt; t += 2) {
;             const bool last = (t == nt - 2);
;             const char* a1 = cA + (size_t)(t + 1) * kstepA;
;             const char* a2 = last ? nA : cA + (size_t)(t + 2) * kstepA; const char* b2 = last ? nB : cB + (size_t)(t + 2) * kstep;
;             const char* a3 = a2 + kstepA; const char* b3 = b2 + kstep;
;             if (last && has_next) S.a_ready(nxt);
;             if constexpr (SP2) {
;             PG8_LDB(B0, 0, 0); PG8_LDB(B1, 0, 1); PG8_SCHED; PG8_LDA(At, 0, 0); PG8_STAGE(PG8_SA(1, 1), a1 + hstep, voffA);
;             PG8_WAIT_V(8); PG8_WAIT_L(0); PG8_BAR; PG8_MMA(0, 0, At, B0); PG8_MMA(0, 1, At, B1); PG8_BAR; PG8_SCHED;
;             PG8_LDA(At, 0, 1); PG8_STAGE(PG8_SB(0, 0), b2, voffB); PG8_STAGE(PG8_SB(0, 1), b2 + hstep, voffB); PG8_STAGE(PG8_SA(0, 0), a2, voffA);
;             PG8_WAIT_V(8); PG8_WAIT_L(0); PG8_BAR; PG8_MMA(1, 0, At, B0); PG8_MMA(1, 1, At, B1); PG8_BAR; PG8_SCHED;
.LBB0_309:
	s_add_u32 s47, s24, 0x100
	s_addc_u32 s48, s25, 0
	s_add_u32 s2, s26, 0x4000
	s_addc_u32 s3, s27, 0
	s_mov_b32 s24, 0
	s_add_i32 s49, s24, 2
	s_add_u32 s25, s2, 0x4000
	s_addc_u32 s26, s3, 0
	s_cmp_eq_u32 s59, s24
	s_cselect_b32 s27, s9, s26
	s_cselect_b32 s26, s8, s25
	s_cselect_b32 s66, s44, s47
	s_cselect_b32 s67, s45, s48
	s_add_u32 s24, s26, 0x4000
	s_addc_u32 s25, s27, 0
	s_add_i32 s65, 0, 0x14000
	v_add_u32_e32 v142, s76, v187
	v_add_u32_e32 v167, s65, v187
	ds_read_b128 v[130:133], v142
	ds_read_b128 v[134:137], v142 offset:1024
	ds_read_b128 v[138:141], v142 offset:2048
	ds_read_b128 v[142:145], v142 offset:3072
	ds_read_b128 v[146:149], v167
	ds_read_b128 v[150:153], v167 offset:1024
	ds_read_b128 v[206:209], v167 offset:2048
	ds_read_b128 v[210:213], v167 offset:3072
	v_lshl_add_u64 v[184:185], s[2:3], 0, v[182:183]
	s_add_i32 m0, s51, 0xc000
	ds_read_b128 v[214:217], v188
	ds_read_b128 v[218:221], v188 offset:1024
	ds_read_b128 v[222:225], v188 offset:2048
	ds_read_b128 v[226:229], v188 offset:3072
	ds_read_b128 v[230:233], v188 offset:4096
	ds_read_b128 v[234:237], v188 offset:5120
	ds_read_b128 v[238:241], v188 offset:6144
	ds_read_b128 v[242:245], v188 offset:7168
	global_load_lds_dwordx4 v[184:185], off
	v_lshl_add_u64 v[184:185], s[2:3], 0, v[180:181]
	s_add_i32 m0, s51, 0xe000
	s_nop 0
	global_load_lds_dwordx4 v[184:185], off
	s_waitcnt vmcnt(8) lgkmcnt(0)
	s_barrier
	v_mfma_f32_16x16x32_bf16 v[126:129], v[130:133], v[214:217], 0
	v_mfma_f32_16x16x32_bf16 v[126:129], v[134:137], v[218:221], v[126:129]
	v_mfma_f32_16x16x32_bf16 v[122:125], v[142:145], v[218:221], 0
	v_mfma_f32_16x16x32_bf16 v[122:125], v[138:141], v[214:217], v[122:125]
	v_mfma_f32_16x16x32_bf16 v[106:109], v[138:141], v[222:225], 0
	v_mfma_f32_16x16x32_bf16 v[106:109], v[142:145], v[226:229], v[106:109]
	v_mfma_f32_16x16x32_bf16 v[110:113], v[134:137], v[226:229], 0
	v_mfma_f32_16x16x32_bf16 v[110:113], v[130:133], v[222:225], v[110:113]
	v_mfma_f32_16x16x32_bf16 v[94:97], v[130:133], v[230:233], 0
	v_mfma_f32_16x16x32_bf16 v[94:97], v[134:137], v[234:237], v[94:97]
	v_mfma_f32_16x16x32_bf16 v[90:93], v[142:145], v[234:237], 0
	v_mfma_f32_16x16x32_bf16 v[90:93], v[138:141], v[230:233], v[90:93]
	v_mfma_f32_16x16x32_bf16 v[74:77], v[138:141], v[238:241], 0
	v_mfma_f32_16x16x32_bf16 v[74:77], v[142:145], v[242:245], v[74:77]
	v_mfma_f32_16x16x32_bf16 v[78:81], v[134:137], v[242:245], 0
	v_mfma_f32_16x16x32_bf16 v[78:81], v[130:133], v[238:241], v[78:81]
	v_mfma_f32_16x16x32_bf16 v[118:121], v[146:149], v[214:217], 0
	v_mfma_f32_16x16x32_bf16 v[118:121], v[150:153], v[218:221], v[118:121]
	v_mfma_f32_16x16x32_bf16 v[114:117], v[210:213], v[218:221], 0
	v_mfma_f32_16x16x32_bf16 v[114:117], v[206:209], v[214:217], v[114:117]
	v_mfma_f32_16x16x32_bf16 v[98:101], v[206:209], v[222:225], 0
	v_mfma_f32_16x16x32_bf16 v[98:101], v[210:213], v[226:229], v[98:101]
	v_mfma_f32_16x16x32_bf16 v[102:105], v[150:153], v[226:229], 0
	v_mfma_f32_16x16x32_bf16 v[102:105], v[146:149], v[222:225], v[102:105]
	v_mfma_f32_16x16x32_bf16 v[86:89], v[146:149], v[230:233], 0
	v_mfma_f32_16x16x32_bf16 v[86:89], v[150:153], v[234:237], v[86:89]
	v_mfma_f32_16x16x32_bf16 v[82:85], v[210:213], v[234:237], 0
	v_mfma_f32_16x16x32_bf16 v[82:85], v[206:209], v[230:233], v[82:85]
	v_mfma_f32_16x16x32_bf16 v[66:69], v[206:209], v[238:241], 0
	v_mfma_f32_16x16x32_bf16 v[66:69], v[210:213], v[242:245], v[66:69]
	v_mfma_f32_16x16x32_bf16 v[70:73], v[150:153], v[242:245], 0
	v_mfma_f32_16x16x32_bf16 v[70:73], v[146:149], v[238:241], v[70:73]
	s_barrier
	s_add_i32 s68, s76, s50
	v_lshl_add_u64 v[184:185], s[66:67], 0, v[0:1]
	s_mov_b32 m0, s68
	ds_read_b128 v[214:217], v188 offset:16384
	ds_read_b128 v[218:221], v188 offset:17408
	ds_read_b128 v[222:225], v188 offset:18432
	ds_read_b128 v[226:229], v188 offset:19456
	ds_read_b128 v[230:233], v188 offset:20480
	ds_read_b128 v[234:237], v188 offset:21504
	ds_read_b128 v[238:241], v188 offset:22528
	ds_read_b128 v[242:245], v188 offset:23552
	global_load_lds_dwordx4 v[184:185], off
	s_add_i32 m0, s68, 0x2000
	v_lshl_add_u64 v[190:191], s[66:67], 0, v[164:165]
	s_add_u32 s66, s66, s12
	s_addc_u32 s67, s67, 0
	s_add_i32 s65, s65, s50
	global_load_lds_dwordx4 v[190:191], off
	v_lshl_add_u64 v[246:247], s[66:67], 0, v[0:1]
	s_mov_b32 m0, s65
	v_lshl_add_u64 v[248:249], s[66:67], 0, v[164:165]
	global_load_lds_dwordx4 v[246:247], off
	s_add_i32 m0, s65, 0x2000
	v_lshl_add_u64 v[250:251], s[26:27], 0, v[160:161]
	global_load_lds_dwordx4 v[248:249], off
	s_mov_b32 m0, s51
	s_nop 0
	global_load_lds_dwordx4 v[250:251], off
	v_lshl_add_u64 v[250:251], s[26:27], 0, v[162:163]
	s_mov_b32 m0, s52
	s_nop 0
	global_load_lds_dwordx4 v[250:251], off
	s_waitcnt vmcnt(8) lgkmcnt(0)
	s_barrier
; #define PG8_STAGE(bufoff, gbase, voff) do { _Pragma("unroll") for (int _i = 0; _i < 2; ++_i) \
;         __builtin_amdgcn_global_load_lds((const unsigned*)((const char*)(gbase) + (voff)[_i]), (PG8_LAS unsigned*)(lds + (bufoff) + ldsw + _i * 8192), 16, 0, 0); } while (0)
; #define PG8_LDA(dst, b, h) do { _Pragma("unroll") for (int m = 0; m < 4; ++m) _Pragma("unroll") for (int k = 0; k < 2; ++k) dst[m][k] = *(const PG8_LAS bf16x8*)(lds + PG8_SA(b, h) + aoff + m * 2048 + k * 1024); } while (0)
; #define PG8_LDB(dst, b, h) do { _Pragma("unroll") for (int n = 0; n < 2; ++n) _Pragma("unroll") for (int k = 0; k < 2; ++k) dst[n][k] = *(const PG8_LAS bf16x8*)(lds + PG8_SB(b, h) + boff + n * 2048 + k * 1024); } while (0)
; #define PG8_MMA(ai, bj, At, Bt) do { __builtin_amdgcn_s_setprio(1); _Pragma("unroll") for (int m = 0; m < 4; ++m) _Pragma("unroll") for (int n = 0; n < 2; ++n) _Pragma("unroll") for (int k = 0; k < 2; ++k) \
;         acc[ai][bj][m][n] = __builtin_amdgcn_mfma_f32_16x16x32_bf16(Bt[n][k], At[m][k], acc[ai][bj][m][n], 0, 0, 0); __builtin_amdgcn_s_setprio(0); } while (0)
; #define PG8_WAIT_V(n) asm volatile("s_waitcnt vmcnt(" #n ")" ::: "memory")
; #define PG8_WAIT_L(n) asm volatile("s_waitcnt lgkmcnt(" #n ")" ::: "memory")
; #define PG8_BAR __builtin_amdgcn_s_barrier()
; #define PG8_SCHED __builtin_amdgcn_sched_barrier(0)
; template <class Epi, class Sched, bool ALIGN_EPI = false, bool SP2 = false>
; __device__ __forceinline__ void gemm_phase(PG8_LAS unsigned char* lds, const Gemm g, const Sched& S, const Epi& E) {
;     ...
;             PG8_WAIT_V(8); PG8_WAIT_L(0); PG8_BAR; PG8_MMA(1, 0, At, B0); PG8_MMA(1, 1, At, B1); PG8_BAR; PG8_SCHED;
;             PG8_LDB(B0, 1, 0); PG8_LDB(B1, 1, 1); PG8_SCHED; PG8_LDA(At, 1, 0); PG8_STAGE(PG8_SA(0, 1), a2 + hstep, voffA);
;             PG8_WAIT_V(8); PG8_WAIT_L(0); PG8_BAR; PG8_MMA(0, 0, At, B0); PG8_MMA(0, 1, At, B1); PG8_BAR; PG8_SCHED;
	v_mfma_f32_16x16x32_bf16 v[62:65], v[130:133], v[214:217], 0
	v_mfma_f32_16x16x32_bf16 v[62:65], v[134:137], v[218:221], v[62:65]
	v_mfma_f32_16x16x32_bf16 v[58:61], v[142:145], v[218:221], 0
	v_mfma_f32_16x16x32_bf16 v[58:61], v[138:141], v[214:217], v[58:61]
	v_mfma_f32_16x16x32_bf16 v[42:45], v[138:141], v[222:225], 0
	v_mfma_f32_16x16x32_bf16 v[42:45], v[142:145], v[226:229], v[42:45]
	v_mfma_f32_16x16x32_bf16 v[46:49], v[134:137], v[226:229], 0
	v_mfma_f32_16x16x32_bf16 v[46:49], v[130:133], v[222:225], v[46:49]
	v_mfma_f32_16x16x32_bf16 v[30:33], v[130:133], v[230:233], 0
	v_mfma_f32_16x16x32_bf16 v[30:33], v[134:137], v[234:237], v[30:33]
	v_mfma_f32_16x16x32_bf16 v[26:29], v[142:145], v[234:237], 0
	v_mfma_f32_16x16x32_bf16 v[26:29], v[138:141], v[230:233], v[26:29]
	v_mfma_f32_16x16x32_bf16 v[10:13], v[138:141], v[238:241], 0
	v_mfma_f32_16x16x32_bf16 v[10:13], v[142:145], v[242:245], v[10:13]
	v_mfma_f32_16x16x32_bf16 v[14:17], v[134:137], v[242:245], 0
	v_mfma_f32_16x16x32_bf16 v[14:17], v[130:133], v[238:241], v[14:17]
	v_mfma_f32_16x16x32_bf16 v[54:57], v[146:149], v[214:217], 0
	v_mfma_f32_16x16x32_bf16 v[54:57], v[150:153], v[218:221], v[54:57]
	v_mfma_f32_16x16x32_bf16 v[50:53], v[210:213], v[218:221], 0
	v_mfma_f32_16x16x32_bf16 v[50:53], v[206:209], v[214:217], v[50:53]
	v_mfma_f32_16x16x32_bf16 v[34:37], v[206:209], v[222:225], 0
	v_mfma_f32_16x16x32_bf16 v[34:37], v[210:213], v[226:229], v[34:37]
	v_mfma_f32_16x16x32_bf16 v[38:41], v[150:153], v[226:229], 0
	v_mfma_f32_16x16x32_bf16 v[38:41], v[146:149], v[222:225], v[38:41]
	v_mfma_f32_16x16x32_bf16 v[22:25], v[146:149], v[230:233], 0
	v_mfma_f32_16x16x32_bf16 v[22:25], v[150:153], v[234:237], v[22:25]
	v_mfma_f32_16x16x32_bf16 v[18:21], v[210:213], v[234:237], 0
	v_mfma_f32_16x16x32_bf16 v[18:21], v[206:209], v[230:233], v[18:21]
	v_mfma_f32_16x16x32_bf16 v[2:5], v[206:209], v[238:241], 0
	v_mfma_f32_16x16x32_bf16 v[2:5], v[210:213], v[242:245], v[2:5]
	v_mfma_f32_16x16x32_bf16 v[6:9], v[150:153], v[242:245], 0
	v_mfma_f32_16x16x32_bf16 v[6:9], v[146:149], v[238:241], v[6:9]
	s_barrier
	s_add_i32 s65, 0, 0x18000
	s_add_i32 s66, 0, 0x1c000
	v_add_u32_e32 v142, s65, v187
	v_add_u32_e32 v167, s66, v187
	ds_read_b128 v[130:133], v142
	ds_read_b128 v[134:137], v142 offset:1024
	ds_read_b128 v[138:141], v142 offset:2048
	ds_read_b128 v[142:145], v142 offset:3072
	ds_read_b128 v[146:149], v167
	ds_read_b128 v[150:153], v167 offset:1024
	ds_read_b128 v[206:209], v167 offset:2048
	ds_read_b128 v[210:213], v167 offset:3072
	s_add_u32 s26, s26, s12
	s_addc_u32 s27, s27, 0
	s_mov_b32 m0, s53
	v_lshl_add_u64 v[250:251], s[26:27], 0, v[160:161]
	ds_read_b128 v[214:217], v188 offset:32768
	ds_read_b128 v[218:221], v188 offset:33792
	ds_read_b128 v[222:225], v188 offset:34816
	ds_read_b128 v[226:229], v188 offset:35840
	ds_read_b128 v[230:233], v188 offset:36864
	ds_read_b128 v[234:237], v188 offset:37888
	ds_read_b128 v[238:241], v188 offset:38912
	ds_read_b128 v[242:245], v188 offset:39936
	global_load_lds_dwordx4 v[250:251], off
	v_lshl_add_u64 v[250:251], s[26:27], 0, v[162:163]
	s_mov_b32 m0, s54
	s_nop 0
	global_load_lds_dwordx4 v[250:251], off
	s_waitcnt vmcnt(8) lgkmcnt(0)
	s_barrier
	v_mfma_f32_16x16x32_bf16 v[126:129], v[130:133], v[214:217], v[126:129]
	v_mfma_f32_16x16x32_bf16 v[126:129], v[134:137], v[218:221], v[126:129]
	v_mfma_f32_16x16x32_bf16 v[122:125], v[142:145], v[218:221], v[122:125]
	v_mfma_f32_16x16x32_bf16 v[122:125], v[138:141], v[214:217], v[122:125]
	v_mfma_f32_16x16x32_bf16 v[106:109], v[138:141], v[222:225], v[106:109]
	v_mfma_f32_16x16x32_bf16 v[106:109], v[142:145], v[226:229], v[106:109]
	v_mfma_f32_16x16x32_bf16 v[110:113], v[134:137], v[226:229], v[110:113]
	v_mfma_f32_16x16x32_bf16 v[110:113], v[130:133], v[222:225], v[110:113]
	v_mfma_f32_16x16x32_bf16 v[94:97], v[130:133], v[230:233], v[94:97]
	v_mfma_f32_16x16x32_bf16 v[94:97], v[134:137], v[234:237], v[94:97]
	v_mfma_f32_16x16x32_bf16 v[90:93], v[142:145], v[234:237], v[90:93]
	v_mfma_f32_16x16x32_bf16 v[90:93], v[138:141], v[230:233], v[90:93]
	v_mfma_f32_16x16x32_bf16 v[74:77], v[138:141], v[238:241], v[74:77]
	v_mfma_f32_16x16x32_bf16 v[74:77], v[142:145], v[242:245], v[74:77]
	v_mfma_f32_16x16x32_bf16 v[78:81], v[134:137], v[242:245], v[78:81]
	v_mfma_f32_16x16x32_bf16 v[78:81], v[130:133], v[238:241], v[78:81]
	v_mfma_f32_16x16x32_bf16 v[118:121], v[146:149], v[214:217], v[118:121]
	v_mfma_f32_16x16x32_bf16 v[118:121], v[150:153], v[218:221], v[118:121]
	v_mfma_f32_16x16x32_bf16 v[114:117], v[210:213], v[218:221], v[114:117]
	v_mfma_f32_16x16x32_bf16 v[114:117], v[206:209], v[214:217], v[114:117]
	v_mfma_f32_16x16x32_bf16 v[98:101], v[206:209], v[222:225], v[98:101]
	v_mfma_f32_16x16x32_bf16 v[98:101], v[210:213], v[226:229], v[98:101]
	v_mfma_f32_16x16x32_bf16 v[102:105], v[150:153], v[226:229], v[102:105]
	v_mfma_f32_16x16x32_bf16 v[102:105], v[146:149], v[222:225], v[102:105]
	v_mfma_f32_16x16x32_bf16 v[86:89], v[146:149], v[230:233], v[86:89]
	v_mfma_f32_16x16x32_bf16 v[86:89], v[150:153], v[234:237], v[86:89]
	v_mfma_f32_16x16x32_bf16 v[82:85], v[210:213], v[234:237], v[82:85]
	v_mfma_f32_16x16x32_bf16 v[82:85], v[206:209], v[230:233], v[82:85]
	v_mfma_f32_16x16x32_bf16 v[66:69], v[206:209], v[238:241], v[66:69]
	v_mfma_f32_16x16x32_bf16 v[66:69], v[210:213], v[242:245], v[66:69]
	v_mfma_f32_16x16x32_bf16 v[70:73], v[150:153], v[242:245], v[70:73]
	v_mfma_f32_16x16x32_bf16 v[70:73], v[146:149], v[238:241], v[70:73]
	s_barrier
; #define PG8_STAGE(bufoff, gbase, voff) do { _Pragma("unroll") for (int _i = 0; _i < 2; ++_i) \
;         __builtin_amdgcn_global_load_lds((const unsigned*)((const char*)(gbase) + (voff)[_i]), (PG8_LAS unsigned*)(lds + (bufoff) + ldsw + _i * 8192), 16, 0, 0); } while (0)
; #define PG8_LDA(dst, b, h) do { _Pragma("unroll") for (int m = 0; m < 4; ++m) _Pragma("unroll") for (int k = 0; k < 2; ++k) dst[m][k] = *(const PG8_LAS bf16x8*)(lds + PG8_SA(b, h) + aoff + m * 2048 + k * 1024); } while (0)
; #define PG8_LDB(dst, b, h) do { _Pragma("unroll") for (int n = 0; n < 2; ++n) _Pragma("unroll") for (int k = 0; k < 2; ++k) dst[n][k] = *(const PG8_LAS bf16x8*)(lds + PG8_SB(b, h) + boff + n * 2048 + k * 1024); } while (0)
; #define PG8_MMA(ai, bj, At, Bt) do { __builtin_amdgcn_s_setprio(1); _Pragma("unroll") for (int m = 0; m < 4; ++m) _Pragma("unroll") for (int n = 0; n < 2; ++n) _Pragma("unroll") for (int k = 0; k < 2; ++k) \
;         acc[ai][bj][m][n] = __builtin_amdgcn_mfma_f32_16x16x32_bf16(Bt[n][k], At[m][k], acc[ai][bj][m][n], 0, 0, 0); __builtin_amdgcn_s_setprio(0); } while (0)
; #define PG8_WAIT_V(n) asm volatile("s_waitcnt vmcnt(" #n ")" ::: "memory")
; #define PG8_BAR __builtin_amdgcn_s_barrier()
; template <class Epi, class Sched, bool ALIGN_EPI = false, bool SP2 = false>
; __device__ __forceinline__ void gemm_phase(PG8_LAS unsigned char* lds, const Gemm g, const Sched& S, const Epi& E) {
;     ...
;         for (int t = 0; t < nt; t += 2) {
;             const bool last = (t == nt - 2);
;             const char* a1 = cA + (size_t)(t + 1) * kstepA;
;             const char* a2 = last ? nA : cA + (size_t)(t + 2) * kstepA; const char* b2 = last ? nB : cB + (size_t)(t + 2) * kstep;
;             const char* a3 = a2 + kstepA; const char* b3 = b2 + kstep;
;             if (last && has_next) S.a_ready(nxt);
;             if constexpr (SP2) {
;             PG8_LDB(B0, 0, 0); PG8_LDB(B1, 0, 1); PG8_SCHED; PG8_LDA(At, 0, 0); PG8_STAGE(PG8_SA(1, 1), a1 + hstep, voffA);
;             PG8_WAIT_V(8); PG8_WAIT_L(0); PG8_BAR; PG8_MMA(0, 0, At, B0); PG8_MMA(0, 1, At, B1); PG8_BAR; PG8_SCHED;
;     ...
;             PG8_LDA(At, 1, 1); PG8_STAGE(PG8_SB(1, 0), b3, voffB); PG8_STAGE(PG8_SB(1, 1), b3 + hstep, voffB); PG8_STAGE(PG8_SA(1, 0), a3, voffA);
;             PG8_WAIT_V(8); PG8_WAIT_L(0); PG8_BAR; PG8_MMA(1, 0, At, B0); PG8_MMA(1, 1, At, B1); PG8_BAR; PG8_SCHED;
	s_add_i32 s26, s65, s50
	v_lshl_add_u64 v[184:185], v[184:185], 0, s[38:39]
	s_mov_b32 m0, s26
	ds_read_b128 v[214:217], v188 offset:49152
	ds_read_b128 v[218:221], v188 offset:50176
	ds_read_b128 v[222:225], v188 offset:51200
	ds_read_b128 v[226:229], v188 offset:52224
	ds_read_b128 v[230:233], v188 offset:53248
	ds_read_b128 v[234:237], v188 offset:54272
	ds_read_b128 v[238:241], v188 offset:55296
	ds_read_b128 v[242:245], v188 offset:56320
	global_load_lds_dwordx4 v[184:185], off
	v_lshl_add_u64 v[184:185], v[190:191], 0, s[38:39]
	s_add_i32 m0, s26, 0x2000
	s_add_i32 s26, s66, s50
	global_load_lds_dwordx4 v[184:185], off
	v_lshl_add_u64 v[184:185], v[246:247], 0, s[38:39]
	s_mov_b32 m0, s26
	s_nop 0
	global_load_lds_dwordx4 v[184:185], off
	v_lshl_add_u64 v[184:185], v[248:249], 0, s[38:39]
	s_add_i32 m0, s26, 0x2000
	s_nop 0
	global_load_lds_dwordx4 v[184:185], off
	v_lshl_add_u64 v[184:185], s[24:25], 0, v[160:161]
	s_mov_b32 m0, s56
	s_nop 0
	global_load_lds_dwordx4 v[184:185], off
	v_lshl_add_u64 v[184:185], s[24:25], 0, v[162:163]
	s_mov_b32 m0, s57
	s_nop 0
	global_load_lds_dwordx4 v[184:185], off
	s_waitcnt vmcnt(8) lgkmcnt(0)
	s_barrier
	v_mfma_f32_16x16x32_bf16 v[62:65], v[130:133], v[214:217], v[62:65]
	v_mfma_f32_16x16x32_bf16 v[62:65], v[134:137], v[218:221], v[62:65]
	v_mfma_f32_16x16x32_bf16 v[58:61], v[142:145], v[218:221], v[58:61]
	v_mfma_f32_16x16x32_bf16 v[58:61], v[138:141], v[214:217], v[58:61]
	v_mfma_f32_16x16x32_bf16 v[42:45], v[138:141], v[222:225], v[42:45]
	v_mfma_f32_16x16x32_bf16 v[42:45], v[142:145], v[226:229], v[42:45]
	v_mfma_f32_16x16x32_bf16 v[46:49], v[134:137], v[226:229], v[46:49]
	v_mfma_f32_16x16x32_bf16 v[46:49], v[130:133], v[222:225], v[46:49]
	v_mfma_f32_16x16x32_bf16 v[30:33], v[130:133], v[230:233], v[30:33]
	v_mfma_f32_16x16x32_bf16 v[30:33], v[134:137], v[234:237], v[30:33]
	v_mfma_f32_16x16x32_bf16 v[26:29], v[142:145], v[234:237], v[26:29]
	v_mfma_f32_16x16x32_bf16 v[26:29], v[138:141], v[230:233], v[26:29]
	v_mfma_f32_16x16x32_bf16 v[10:13], v[138:141], v[238:241], v[10:13]
	v_mfma_f32_16x16x32_bf16 v[10:13], v[142:145], v[242:245], v[10:13]
	v_mfma_f32_16x16x32_bf16 v[14:17], v[134:137], v[242:245], v[14:17]
	v_mfma_f32_16x16x32_bf16 v[14:17], v[130:133], v[238:241], v[14:17]
	v_mfma_f32_16x16x32_bf16 v[54:57], v[146:149], v[214:217], v[54:57]
	v_mfma_f32_16x16x32_bf16 v[54:57], v[150:153], v[218:221], v[54:57]
	v_mfma_f32_16x16x32_bf16 v[50:53], v[210:213], v[218:221], v[50:53]
	v_mfma_f32_16x16x32_bf16 v[50:53], v[206:209], v[214:217], v[50:53]
	v_mfma_f32_16x16x32_bf16 v[34:37], v[206:209], v[222:225], v[34:37]
	v_mfma_f32_16x16x32_bf16 v[34:37], v[210:213], v[226:229], v[34:37]
	v_mfma_f32_16x16x32_bf16 v[38:41], v[150:153], v[226:229], v[38:41]
	v_mfma_f32_16x16x32_bf16 v[38:41], v[146:149], v[222:225], v[38:41]
	v_mfma_f32_16x16x32_bf16 v[22:25], v[146:149], v[230:233], v[22:25]
	v_mfma_f32_16x16x32_bf16 v[22:25], v[150:153], v[234:237], v[22:25]
	v_mfma_f32_16x16x32_bf16 v[18:21], v[210:213], v[234:237], v[18:21]
	v_mfma_f32_16x16x32_bf16 v[18:21], v[206:209], v[230:233], v[18:21]
	v_mfma_f32_16x16x32_bf16 v[2:5], v[206:209], v[238:241], v[2:5]
	v_mfma_f32_16x16x32_bf16 v[2:5], v[210:213], v[242:245], v[2:5]
	v_mfma_f32_16x16x32_bf16 v[6:9], v[150:153], v[242:245], v[6:9]
	v_mfma_f32_16x16x32_bf16 v[6:9], v[146:149], v[238:241], v[6:9]
	s_barrier
	s_add_u32 s47, s47, 0x100
	s_addc_u32 s48, s48, 0
	s_add_u32 s2, s2, 0x8000
	s_addc_u32 s3, s3, 0
	s_cmp_ge_u32 s49, s55
	s_mov_b32 s24, s49
	s_cbranch_scc1 .Lpeel_exit_1
.LBB0_310:
	s_add_i32 s49, s24, 2
	s_add_u32 s25, s2, 0x4000
	s_addc_u32 s26, s3, 0
	s_cmp_eq_u32 s59, s24
	s_cselect_b32 s27, s9, s26
	s_cselect_b32 s26, s8, s25
	s_cselect_b32 s66, s44, s47
	s_cselect_b32 s67, s45, s48
	s_add_u32 s24, s26, 0x4000
	s_addc_u32 s25, s27, 0
	s_add_i32 s65, 0, 0x14000
	v_add_u32_e32 v142, s76, v187
	v_add_u32_e32 v167, s65, v187
	ds_read_b128 v[130:133], v142
	ds_read_b128 v[134:137], v142 offset:1024
	ds_read_b128 v[138:141], v142 offset:2048
	ds_read_b128 v[142:145], v142 offset:3072
	ds_read_b128 v[146:149], v167
	ds_read_b128 v[150:153], v167 offset:1024
	ds_read_b128 v[206:209], v167 offset:2048
	ds_read_b128 v[210:213], v167 offset:3072
	v_lshl_add_u64 v[184:185], s[2:3], 0, v[182:183]
	s_add_i32 m0, s51, 0xc000
	ds_read_b128 v[214:217], v188
	ds_read_b128 v[218:221], v188 offset:1024
	ds_read_b128 v[222:225], v188 offset:2048
	ds_read_b128 v[226:229], v188 offset:3072
	ds_read_b128 v[230:233], v188 offset:4096
	ds_read_b128 v[234:237], v188 offset:5120
	ds_read_b128 v[238:241], v188 offset:6144
	ds_read_b128 v[242:245], v188 offset:7168
	global_load_lds_dwordx4 v[184:185], off
	v_lshl_add_u64 v[184:185], s[2:3], 0, v[180:181]
	s_add_i32 m0, s51, 0xe000
	s_nop 0
	global_load_lds_dwordx4 v[184:185], off
	s_waitcnt vmcnt(8) lgkmcnt(0)
	s_barrier
; #define PG8_STAGE(bufoff, gbase, voff) do { _Pragma("unroll") for (int _i = 0; _i < 2; ++_i) \
;         __builtin_amdgcn_global_load_lds((const unsigned*)((const char*)(gbase) + (voff)[_i]), (PG8_LAS unsigned*)(lds + (bufoff) + ldsw + _i * 8192), 16, 0, 0); } while (0)
; #define PG8_LDA(dst, b, h) do { _Pragma("unroll") for (int m = 0; m < 4; ++m) _Pragma("unroll") for (int k = 0; k < 2; ++k) dst[m][k] = *(const PG8_LAS bf16x8*)(lds + PG8_SA(b, h) + aoff + m * 2048 + k * 1024); } while (0)
; #define PG8_MMA(ai, bj, At, Bt) do { __builtin_amdgcn_s_setprio(1); _Pragma("unroll") for (int m = 0; m < 4; ++m) _Pragma("unroll") for (int n = 0; n < 2; ++n) _Pragma("unroll") for (int k = 0; k < 2; ++k) \
;         acc[ai][bj][m][n] = __builtin_amdgcn_mfma_f32_16x16x32_bf16(Bt[n][k], At[m][k], acc[ai][bj][m][n], 0, 0, 0); __builtin_amdgcn_s_setprio(0); } while (0)
; #define PG8_WAIT_V(n) asm volatile("s_waitcnt vmcnt(" #n ")" ::: "memory")
; #define PG8_WAIT_L(n) asm volatile("s_waitcnt lgkmcnt(" #n ")" ::: "memory")
; #define PG8_BAR __builtin_amdgcn_s_barrier()
; #define PG8_SCHED __builtin_amdgcn_sched_barrier(0)
; template <class Epi, class Sched, bool ALIGN_EPI = false, bool SP2 = false>
; __device__ __forceinline__ void gemm_phase(PG8_LAS unsigned char* lds, const Gemm g, const Sched& S, const Epi& E) {
;     ...
;             PG8_WAIT_V(8); PG8_WAIT_L(0); PG8_BAR; PG8_MMA(0, 0, At, B0); PG8_MMA(0, 1, At, B1); PG8_BAR; PG8_SCHED;
;             PG8_LDA(At, 0, 1); PG8_STAGE(PG8_SB(0, 0), b2, voffB); PG8_STAGE(PG8_SB(0, 1), b2 + hstep, voffB); PG8_STAGE(PG8_SA(0, 0), a2, voffA);
;             PG8_WAIT_V(8); PG8_WAIT_L(0); PG8_BAR; PG8_MMA(1, 0, At, B0); PG8_MMA(1, 1, At, B1); PG8_BAR; PG8_SCHED;
	v_mfma_f32_16x16x32_bf16 v[126:129], v[130:133], v[214:217], v[126:129]
	v_mfma_f32_16x16x32_bf16 v[126:129], v[134:137], v[218:221], v[126:129]
	v_mfma_f32_16x16x32_bf16 v[122:125], v[142:145], v[218:221], v[122:125]
	v_mfma_f32_16x16x32_bf16 v[122:125], v[138:141], v[214:217], v[122:125]
	v_mfma_f32_16x16x32_bf16 v[106:109], v[138:141], v[222:225], v[106:109]
	v_mfma_f32_16x16x32_bf16 v[106:109], v[142:145], v[226:229], v[106:109]
	v_mfma_f32_16x16x32_bf16 v[110:113], v[134:137], v[226:229], v[110:113]
	v_mfma_f32_16x16x32_bf16 v[110:113], v[130:133], v[222:225], v[110:113]
	v_mfma_f32_16x16x32_bf16 v[94:97], v[130:133], v[230:233], v[94:97]
	v_mfma_f32_16x16x32_bf16 v[94:97], v[134:137], v[234:237], v[94:97]
	v_mfma_f32_16x16x32_bf16 v[90:93], v[142:145], v[234:237], v[90:93]
	v_mfma_f32_16x16x32_bf16 v[90:93], v[138:141], v[230:233], v[90:93]
	v_mfma_f32_16x16x32_bf16 v[74:77], v[138:141], v[238:241], v[74:77]
	v_mfma_f32_16x16x32_bf16 v[74:77], v[142:145], v[242:245], v[74:77]
	v_mfma_f32_16x16x32_bf16 v[78:81], v[134:137], v[242:245], v[78:81]
	v_mfma_f32_16x16x32_bf16 v[78:81], v[130:133], v[238:241], v[78:81]
	v_mfma_f32_16x16x32_bf16 v[118:121], v[146:149], v[214:217], v[118:121]
	v_mfma_f32_16x16x32_bf16 v[118:121], v[150:153], v[218:221], v[118:121]
	v_mfma_f32_16x16x32_bf16 v[114:117], v[210:213], v[218:221], v[114:117]
	v_mfma_f32_16x16x32_bf16 v[114:117], v[206:209], v[214:217], v[114:117]
	v_mfma_f32_16x16x32_bf16 v[98:101], v[206:209], v[222:225], v[98:101]
	v_mfma_f32_16x16x32_bf16 v[98:101], v[210:213], v[226:229], v[98:101]
	v_mfma_f32_16x16x32_bf16 v[102:105], v[150:153], v[226:229], v[102:105]
	v_mfma_f32_16x16x32_bf16 v[102:105], v[146:149], v[222:225], v[102:105]
	v_mfma_f32_16x16x32_bf16 v[86:89], v[146:149], v[230:233], v[86:89]
	v_mfma_f32_16x16x32_bf16 v[86:89], v[150:153], v[234:237], v[86:89]
	v_mfma_f32_16x16x32_bf16 v[82:85], v[210:213], v[234:237], v[82:85]
	v_mfma_f32_16x16x32_bf16 v[82:85], v[206:209], v[230:233], v[82:85]
	v_mfma_f32_16x16x32_bf16 v[66:69], v[206:209], v[238:241], v[66:69]
	v_mfma_f32_16x16x32_bf16 v[66:69], v[210:213], v[242:245], v[66:69]
	v_mfma_f32_16x16x32_bf16 v[70:73], v[150:153], v[242:245], v[70:73]
	v_mfma_f32_16x16x32_bf16 v[70:73], v[146:149], v[238:241], v[70:73]
	s_barrier
	s_add_i32 s68, s76, s50
	v_lshl_add_u64 v[184:185], s[66:67], 0, v[0:1]
	s_mov_b32 m0, s68
	ds_read_b128 v[214:217], v188 offset:16384
	ds_read_b128 v[218:221], v188 offset:17408
	ds_read_b128 v[222:225], v188 offset:18432
	ds_read_b128 v[226:229], v188 offset:19456
	ds_read_b128 v[230:233], v188 offset:20480
	ds_read_b128 v[234:237], v188 offset:21504
	ds_read_b128 v[238:241], v188 offset:22528
	ds_read_b128 v[242:245], v188 offset:23552
	global_load_lds_dwordx4 v[184:185], off
	s_add_i32 m0, s68, 0x2000
	v_lshl_add_u64 v[190:191], s[66:67], 0, v[164:165]
	s_add_u32 s66, s66, s12
	s_addc_u32 s67, s67, 0
	s_add_i32 s65, s65, s50
	global_load_lds_dwordx4 v[190:191], off
	v_lshl_add_u64 v[246:247], s[66:67], 0, v[0:1]
	s_mov_b32 m0, s65
	v_lshl_add_u64 v[248:249], s[66:67], 0, v[164:165]
	global_load_lds_dwordx4 v[246:247], off
	s_add_i32 m0, s65, 0x2000
	v_lshl_add_u64 v[250:251], s[26:27], 0, v[160:161]
	global_load_lds_dwordx4 v[248:249], off
	s_mov_b32 m0, s51
	s_nop 0
	global_load_lds_dwordx4 v[250:251], off
	v_lshl_add_u64 v[250:251], s[26:27], 0, v[162:163]
	s_mov_b32 m0, s52
	s_nop 0
	global_load_lds_dwordx4 v[250:251], off
	s_waitcnt vmcnt(8) lgkmcnt(0)
	s_barrier
	v_mfma_f32_16x16x32_bf16 v[62:65], v[130:133], v[214:217], v[62:65]
	v_mfma_f32_16x16x32_bf16 v[62:65], v[134:137], v[218:221], v[62:65]
	v_mfma_f32_16x16x32_bf16 v[58:61], v[142:145], v[218:221], v[58:61]
	v_mfma_f32_16x16x32_bf16 v[58:61], v[138:141], v[214:217], v[58:61]
	v_mfma_f32_16x16x32_bf16 v[42:45], v[138:141], v[222:225], v[42:45]
	v_mfma_f32_16x16x32_bf16 v[42:45], v[142:145], v[226:229], v[42:45]
	v_mfma_f32_16x16x32_bf16 v[46:49], v[134:137], v[226:229], v[46:49]
	v_mfma_f32_16x16x32_bf16 v[46:49], v[130:133], v[222:225], v[46:49]
	v_mfma_f32_16x16x32_bf16 v[30:33], v[130:133], v[230:233], v[30:33]
	v_mfma_f32_16x16x32_bf16 v[30:33], v[134:137], v[234:237], v[30:33]
	v_mfma_f32_16x16x32_bf16 v[26:29], v[142:145], v[234:237], v[26:29]
	v_mfma_f32_16x16x32_bf16 v[26:29], v[138:141], v[230:233], v[26:29]
	v_mfma_f32_16x16x32_bf16 v[10:13], v[138:141], v[238:241], v[10:13]
	v_mfma_f32_16x16x32_bf16 v[10:13], v[142:145], v[242:245], v[10:13]
	v_mfma_f32_16x16x32_bf16 v[14:17], v[134:137], v[242:245], v[14:17]
	v_mfma_f32_16x16x32_bf16 v[14:17], v[130:133], v[238:241], v[14:17]
	v_mfma_f32_16x16x32_bf16 v[54:57], v[146:149], v[214:217], v[54:57]
	v_mfma_f32_16x16x32_bf16 v[54:57], v[150:153], v[218:221], v[54:57]
	v_mfma_f32_16x16x32_bf16 v[50:53], v[210:213], v[218:221], v[50:53]
	v_mfma_f32_16x16x32_bf16 v[50:53], v[206:209], v[214:217], v[50:53]
	v_mfma_f32_16x16x32_bf16 v[34:37], v[206:209], v[222:225], v[34:37]
	v_mfma_f32_16x16x32_bf16 v[34:37], v[210:213], v[226:229], v[34:37]
	v_mfma_f32_16x16x32_bf16 v[38:41], v[150:153], v[226:229], v[38:41]
	v_mfma_f32_16x16x32_bf16 v[38:41], v[146:149], v[222:225], v[38:41]
	v_mfma_f32_16x16x32_bf16 v[22:25], v[146:149], v[230:233], v[22:25]
	v_mfma_f32_16x16x32_bf16 v[22:25], v[150:153], v[234:237], v[22:25]
	v_mfma_f32_16x16x32_bf16 v[18:21], v[210:213], v[234:237], v[18:21]
	v_mfma_f32_16x16x32_bf16 v[18:21], v[206:209], v[230:233], v[18:21]
	v_mfma_f32_16x16x32_bf16 v[2:5], v[206:209], v[238:241], v[2:5]
	v_mfma_f32_16x16x32_bf16 v[2:5], v[210:213], v[242:245], v[2:5]
	v_mfma_f32_16x16x32_bf16 v[6:9], v[150:153], v[242:245], v[6:9]
	v_mfma_f32_16x16x32_bf16 v[6:9], v[146:149], v[238:241], v[6:9]
	s_barrier
; #define PG8_STAGE(bufoff, gbase, voff) do { _Pragma("unroll") for (int _i = 0; _i < 2; ++_i) \
;         __builtin_amdgcn_global_load_lds((const unsigned*)((const char*)(gbase) + (voff)[_i]), (PG8_LAS unsigned*)(lds + (bufoff) + ldsw + _i * 8192), 16, 0, 0); } while (0)
; #define PG8_LDA(dst, b, h) do { _Pragma("unroll") for (int m = 0; m < 4; ++m) _Pragma("unroll") for (int k = 0; k < 2; ++k) dst[m][k] = *(const PG8_LAS bf16x8*)(lds + PG8_SA(b, h) + aoff + m * 2048 + k * 1024); } while (0)
; #define PG8_LDB(dst, b, h) do { _Pragma("unroll") for (int n = 0; n < 2; ++n) _Pragma("unroll") for (int k = 0; k < 2; ++k) dst[n][k] = *(const PG8_LAS bf16x8*)(lds + PG8_SB(b, h) + boff + n * 2048 + k * 1024); } while (0)
; #define PG8_MMA(ai, bj, At, Bt) do { __builtin_amdgcn_s_setprio(1); _Pragma("unroll") for (int m = 0; m < 4; ++m) _Pragma("unroll") for (int n = 0; n < 2; ++n) _Pragma("unroll") for (int k = 0; k < 2; ++k) \
;         acc[ai][bj][m][n] = __builtin_amdgcn_mfma_f32_16x16x32_bf16(Bt[n][k], At[m][k], acc[ai][bj][m][n], 0, 0, 0); __builtin_amdgcn_s_setprio(0); } while (0)
; #define PG8_WAIT_V(n) asm volatile("s_waitcnt vmcnt(" #n ")" ::: "memory")
; #define PG8_WAIT_L(n) asm volatile("s_waitcnt lgkmcnt(" #n ")" ::: "memory")
; #define PG8_BAR __builtin_amdgcn_s_barrier()
; #define PG8_SCHED __builtin_amdgcn_sched_barrier(0)
; template <class Epi, class Sched, bool ALIGN_EPI = false, bool SP2 = false>
; __device__ __forceinline__ void gemm_phase(PG8_LAS unsigned char* lds, const Gemm g, const Sched& S, const Epi& E) {
;     ...
;             PG8_LDB(B0, 1, 0); PG8_LDB(B1, 1, 1); PG8_SCHED; PG8_LDA(At, 1, 0); PG8_STAGE(PG8_SA(0, 1), a2 + hstep, voffA);
;             PG8_WAIT_V(8); PG8_WAIT_L(0); PG8_BAR; PG8_MMA(0, 0, At, B0); PG8_MMA(0, 1, At, B1); PG8_BAR; PG8_SCHED;
;             PG8_LDA(At, 1, 1); PG8_STAGE(PG8_SB(1, 0), b3, voffB); PG8_STAGE(PG8_SB(1, 1), b3 + hstep, voffB); PG8_STAGE(PG8_SA(1, 0), a3, voffA);
;             PG8_WAIT_V(8); PG8_WAIT_L(0); PG8_BAR; PG8_MMA(1, 0, At, B0); PG8_MMA(1, 1, At, B1); PG8_BAR; PG8_SCHED;
	s_add_i32 s65, 0, 0x18000
	s_add_i32 s66, 0, 0x1c000
	v_add_u32_e32 v142, s65, v187
	v_add_u32_e32 v167, s66, v187
	ds_read_b128 v[130:133], v142
	ds_read_b128 v[134:137], v142 offset:1024
	ds_read_b128 v[138:141], v142 offset:2048
	ds_read_b128 v[142:145], v142 offset:3072
	ds_read_b128 v[146:149], v167
	ds_read_b128 v[150:153], v167 offset:1024
	ds_read_b128 v[206:209], v167 offset:2048
	ds_read_b128 v[210:213], v167 offset:3072
	s_add_u32 s26, s26, s12
	s_addc_u32 s27, s27, 0
	s_mov_b32 m0, s53
	v_lshl_add_u64 v[250:251], s[26:27], 0, v[160:161]
	ds_read_b128 v[214:217], v188 offset:32768
	ds_read_b128 v[218:221], v188 offset:33792
	ds_read_b128 v[222:225], v188 offset:34816
	ds_read_b128 v[226:229], v188 offset:35840
	ds_read_b128 v[230:233], v188 offset:36864
	ds_read_b128 v[234:237], v188 offset:37888
	ds_read_b128 v[238:241], v188 offset:38912
	ds_read_b128 v[242:245], v188 offset:39936
	global_load_lds_dwordx4 v[250:251], off
	v_lshl_add_u64 v[250:251], s[26:27], 0, v[162:163]
	s_mov_b32 m0, s54
	s_nop 0
	global_load_lds_dwordx4 v[250:251], off
	s_waitcnt vmcnt(8) lgkmcnt(0)
	s_barrier
	v_mfma_f32_16x16x32_bf16 v[126:129], v[130:133], v[214:217], v[126:129]
	v_mfma_f32_16x16x32_bf16 v[126:129], v[134:137], v[218:221], v[126:129]
	v_mfma_f32_16x16x32_bf16 v[122:125], v[142:145], v[218:221], v[122:125]
	v_mfma_f32_16x16x32_bf16 v[122:125], v[138:141], v[214:217], v[122:125]
	v_mfma_f32_16x16x32_bf16 v[106:109], v[138:141], v[222:225], v[106:109]
	v_mfma_f32_16x16x32_bf16 v[106:109], v[142:145], v[226:229], v[106:109]
	v_mfma_f32_16x16x32_bf16 v[110:113], v[134:137], v[226:229], v[110:113]
	v_mfma_f32_16x16x32_bf16 v[110:113], v[130:133], v[222:225], v[110:113]
	v_mfma_f32_16x16x32_bf16 v[94:97], v[130:133], v[230:233], v[94:97]
	v_mfma_f32_16x16x32_bf16 v[94:97], v[134:137], v[234:237], v[94:97]
	v_mfma_f32_16x16x32_bf16 v[90:93], v[142:145], v[234:237], v[90:93]
	v_mfma_f32_16x16x32_bf16 v[90:93], v[138:141], v[230:233], v[90:93]
	v_mfma_f32_16x16x32_bf16 v[74:77], v[138:141], v[238:241], v[74:77]
	v_mfma_f32_16x16x32_bf16 v[74:77], v[142:145], v[242:245], v[74:77]
	v_mfma_f32_16x16x32_bf16 v[78:81], v[134:137], v[242:245], v[78:81]
	v_mfma_f32_16x16x32_bf16 v[78:81], v[130:133], v[238:241], v[78:81]
	v_mfma_f32_16x16x32_bf16 v[118:121], v[146:149], v[214:217], v[118:121]
	v_mfma_f32_16x16x32_bf16 v[118:121], v[150:153], v[218:221], v[118:121]
	v_mfma_f32_16x16x32_bf16 v[114:117], v[210:213], v[218:221], v[114:117]
	v_mfma_f32_16x16x32_bf16 v[114:117], v[206:209], v[214:217], v[114:117]
	v_mfma_f32_16x16x32_bf16 v[98:101], v[206:209], v[222:225], v[98:101]
	v_mfma_f32_16x16x32_bf16 v[98:101], v[210:213], v[226:229], v[98:101]
	v_mfma_f32_16x16x32_bf16 v[102:105], v[150:153], v[226:229], v[102:105]
	v_mfma_f32_16x16x32_bf16 v[102:105], v[146:149], v[222:225], v[102:105]
	v_mfma_f32_16x16x32_bf16 v[86:89], v[146:149], v[230:233], v[86:89]
	v_mfma_f32_16x16x32_bf16 v[86:89], v[150:153], v[234:237], v[86:89]
	v_mfma_f32_16x16x32_bf16 v[82:85], v[210:213], v[234:237], v[82:85]
	v_mfma_f32_16x16x32_bf16 v[82:85], v[206:209], v[230:233], v[82:85]
	v_mfma_f32_16x16x32_bf16 v[66:69], v[206:209], v[238:241], v[66:69]
	v_mfma_f32_16x16x32_bf16 v[66:69], v[210:213], v[242:245], v[66:69]
	v_mfma_f32_16x16x32_bf16 v[70:73], v[150:153], v[242:245], v[70:73]
	v_mfma_f32_16x16x32_bf16 v[70:73], v[146:149], v[238:241], v[70:73]
	s_barrier
	s_add_i32 s26, s65, s50
	v_lshl_add_u64 v[184:185], v[184:185], 0, s[38:39]
	s_mov_b32 m0, s26
	ds_read_b128 v[214:217], v188 offset:49152
	ds_read_b128 v[218:221], v188 offset:50176
	ds_read_b128 v[222:225], v188 offset:51200
	ds_read_b128 v[226:229], v188 offset:52224
	ds_read_b128 v[230:233], v188 offset:53248
	ds_read_b128 v[234:237], v188 offset:54272
	ds_read_b128 v[238:241], v188 offset:55296
	ds_read_b128 v[242:245], v188 offset:56320
	global_load_lds_dwordx4 v[184:185], off
	v_lshl_add_u64 v[184:185], v[190:191], 0, s[38:39]
	s_add_i32 m0, s26, 0x2000
	s_add_i32 s26, s66, s50
	global_load_lds_dwordx4 v[184:185], off
	v_lshl_add_u64 v[184:185], v[246:247], 0, s[38:39]
	s_mov_b32 m0, s26
	s_nop 0
	global_load_lds_dwordx4 v[184:185], off
	v_lshl_add_u64 v[184:185], v[248:249], 0, s[38:39]
	s_add_i32 m0, s26, 0x2000
	s_nop 0
	global_load_lds_dwordx4 v[184:185], off
	v_lshl_add_u64 v[184:185], s[24:25], 0, v[160:161]
	s_mov_b32 m0, s56
	s_nop 0
	global_load_lds_dwordx4 v[184:185], off
	v_lshl_add_u64 v[184:185], s[24:25], 0, v[162:163]
	s_mov_b32 m0, s57
	s_nop 0
	global_load_lds_dwordx4 v[184:185], off
	s_waitcnt vmcnt(8) lgkmcnt(0)
	s_barrier
	v_mfma_f32_16x16x32_bf16 v[62:65], v[130:133], v[214:217], v[62:65]
	v_mfma_f32_16x16x32_bf16 v[62:65], v[134:137], v[218:221], v[62:65]
	v_mfma_f32_16x16x32_bf16 v[58:61], v[142:145], v[218:221], v[58:61]
	v_mfma_f32_16x16x32_bf16 v[58:61], v[138:141], v[214:217], v[58:61]
	v_mfma_f32_16x16x32_bf16 v[42:45], v[138:141], v[222:225], v[42:45]
	v_mfma_f32_16x16x32_bf16 v[42:45], v[142:145], v[226:229], v[42:45]
	v_mfma_f32_16x16x32_bf16 v[46:49], v[134:137], v[226:229], v[46:49]
	v_mfma_f32_16x16x32_bf16 v[46:49], v[130:133], v[222:225], v[46:49]
	v_mfma_f32_16x16x32_bf16 v[30:33], v[130:133], v[230:233], v[30:33]
	v_mfma_f32_16x16x32_bf16 v[30:33], v[134:137], v[234:237], v[30:33]
	v_mfma_f32_16x16x32_bf16 v[26:29], v[142:145], v[234:237], v[26:29]
	v_mfma_f32_16x16x32_bf16 v[26:29], v[138:141], v[230:233], v[26:29]
	v_mfma_f32_16x16x32_bf16 v[10:13], v[138:141], v[238:241], v[10:13]
	v_mfma_f32_16x16x32_bf16 v[10:13], v[142:145], v[242:245], v[10:13]
	v_mfma_f32_16x16x32_bf16 v[14:17], v[134:137], v[242:245], v[14:17]
	v_mfma_f32_16x16x32_bf16 v[14:17], v[130:133], v[238:241], v[14:17]
	v_mfma_f32_16x16x32_bf16 v[54:57], v[146:149], v[214:217], v[54:57]
	v_mfma_f32_16x16x32_bf16 v[54:57], v[150:153], v[218:221], v[54:57]
	v_mfma_f32_16x16x32_bf16 v[50:53], v[210:213], v[218:221], v[50:53]
	v_mfma_f32_16x16x32_bf16 v[50:53], v[206:209], v[214:217], v[50:53]
	v_mfma_f32_16x16x32_bf16 v[34:37], v[206:209], v[222:225], v[34:37]
	v_mfma_f32_16x16x32_bf16 v[34:37], v[210:213], v[226:229], v[34:37]
	v_mfma_f32_16x16x32_bf16 v[38:41], v[150:153], v[226:229], v[38:41]
	v_mfma_f32_16x16x32_bf16 v[38:41], v[146:149], v[222:225], v[38:41]
	v_mfma_f32_16x16x32_bf16 v[22:25], v[146:149], v[230:233], v[22:25]
	v_mfma_f32_16x16x32_bf16 v[22:25], v[150:153], v[234:237], v[22:25]
	v_mfma_f32_16x16x32_bf16 v[18:21], v[210:213], v[234:237], v[18:21]
	v_mfma_f32_16x16x32_bf16 v[18:21], v[206:209], v[230:233], v[18:21]
	v_mfma_f32_16x16x32_bf16 v[2:5], v[206:209], v[238:241], v[2:5]
	v_mfma_f32_16x16x32_bf16 v[2:5], v[210:213], v[242:245], v[2:5]
	v_mfma_f32_16x16x32_bf16 v[6:9], v[150:153], v[242:245], v[6:9]
	v_mfma_f32_16x16x32_bf16 v[6:9], v[146:149], v[238:241], v[6:9]
	s_barrier
	s_add_u32 s47, s47, 0x100
	s_addc_u32 s48, s48, 0
	s_add_u32 s2, s2, 0x8000
	s_addc_u32 s3, s3, 0
	s_cmp_ge_u32 s49, s55
	s_mov_b32 s24, s49
	s_cbranch_scc0 .LBB0_310

; #define PG8_STAGE(bufoff, gbase, voff) do { _Pragma("unroll") for (int _i = 0; _i < 2; ++_i) \
;         __builtin_amdgcn_global_load_lds((const unsigned*)((const char*)(gbase) + (voff)[_i]), (PG8_LAS unsigned*)(lds + (bufoff) + ldsw + _i * 8192), 16, 0, 0); } while (0)
; #define PG8_LDA(dst, b, h) do { _Pragma("unroll") for (int m = 0; m < 4; ++m) _Pragma("unroll") for (int k = 0; k < 2; ++k) dst[m][k] = *(const PG8_LAS bf16x8*)(lds + PG8_SA(b, h) + aoff + m * 2048 + k * 1024); } while (0)
; #define PG8_LDB(dst, b, h) do { _Pragma("unroll") for (int n = 0; n < 2; ++n) _Pragma("unroll") for (int k = 0; k < 2; ++k) dst[n][k] = *(const PG8_LAS bf16x8*)(lds + PG8_SB(b, h) + boff + n * 2048 + k * 1024); } while (0)
; #define PG8_WAIT_V(n) asm volatile("s_waitcnt vmcnt(" #n ")" ::: "memory")
; #define PG8_WAIT_L(n) asm volatile("s_waitcnt lgkmcnt(" #n ")" ::: "memory")
; #define PG8_BAR __builtin_amdgcn_s_barrier()
; #define PG8_SCHED __builtin_amdgcn_sched_barrier(0)
; template <class Epi, class Sched, bool ALIGN_EPI = false, bool SP2 = false>
; __device__ __forceinline__ void gemm_phase(PG8_LAS unsigned char* lds, const Gemm g, const Sched& S, const Epi& E) {
;     ...
;         const char* nA = has_next ? (const char*)g.A + (size_t)nxt.pm * tstep : cA; const char* nB = has_next ? (const char*)g.Bt + (size_t)nxt.pn * tstep : cB;
;         for (int t = 0; t < nt; t += 2) {
;             const bool last = (t == nt - 2);
;             const char* a1 = cA + (size_t)(t + 1) * kstepA;
;             const char* a2 = last ? nA : cA + (size_t)(t + 2) * kstepA; const char* b2 = last ? nB : cB + (size_t)(t + 2) * kstep;
;             const char* a3 = a2 + kstepA; const char* b3 = b2 + kstep;
;             if (last && has_next) S.a_ready(nxt);
;             if constexpr (SP2) {
;             PG8_LDB(B0, 0, 0); PG8_LDB(B1, 0, 1); PG8_SCHED; PG8_LDA(At, 0, 0); PG8_STAGE(PG8_SA(1, 1), a1 + hstep, voffA);
;             PG8_WAIT_V(8); PG8_WAIT_L(0); PG8_BAR; PG8_MMA(0, 0, At, B0); PG8_MMA(0, 1, At, B1); PG8_BAR; PG8_SCHED;
;             PG8_LDA(At, 0, 1); PG8_STAGE(PG8_SB(0, 0), b2, voffB); PG8_STAGE(PG8_SB(0, 1), b2 + hstep, voffB); PG8_STAGE(PG8_SA(0, 0), a2, voffA);
;             PG8_WAIT_V(8); PG8_WAIT_L(0); PG8_BAR; PG8_MMA(1, 0, At, B0); PG8_MMA(1, 1, At, B1); PG8_BAR; PG8_SCHED;
.LBB0_408:
	s_ashr_i32 s11, s10, 31
	s_lshl_b64 s[12:13], s[10:11], 19
	s_add_u32 s12, s30, s12
	s_addc_u32 s13, s31, s13
	s_and_b64 s[18:19], s[4:5], exec
	s_cselect_b32 s11, s13, s23
	s_cselect_b32 s53, s12, s22
	s_ashr_i32 s9, s8, 31
	s_lshl_b64 s[18:19], s[8:9], 19
	s_add_u32 s18, s37, s18
	s_addc_u32 s19, s44, s19
	s_and_b64 s[26:27], s[4:5], exec
	s_cselect_b32 s9, s19, s25
	s_cselect_b32 s54, s18, s24
	s_add_u32 s55, s24, 0x100
	s_addc_u32 s56, s25, 0
	s_mov_b32 s57, -2
	s_add_u32 s24, s22, 0x8000
	s_addc_u32 s25, s23, 0
	s_cmp_eq_u32 s57, 12
	s_cselect_b32 s42, s53, s24
	s_cselect_b32 s43, s11, s25
	s_cselect_b32 s40, s54, s55
	s_cselect_b32 s41, s9, s56
	s_add_u32 s26, s42, 0x4000
	s_addc_u32 s27, s43, 0
	v_add_u32_e32 v145, s76, v142
	s_add_i32 s58, 0, 0x14000
	ds_read_b128 v[146:149], v145
	ds_read_b128 v[150:153], v145 offset:1024
	ds_read_b128 v[160:163], v145 offset:2048
	ds_read_b128 v[164:167], v145 offset:3072
	v_add_u32_e32 v145, s58, v142
	ds_read_b128 v[168:171], v145
	ds_read_b128 v[172:175], v145 offset:1024
	ds_read_b128 v[176:179], v145 offset:2048
	ds_read_b128 v[180:183], v145 offset:3072
	v_lshl_add_u64 v[230:231], s[22:23], 0, v[140:141]
	s_add_i32 m0, s45, 0xc000
	ds_read_b128 v[184:187], v144
	ds_read_b128 v[188:191], v144 offset:1024
	ds_read_b128 v[206:209], v144 offset:2048
	ds_read_b128 v[210:213], v144 offset:3072
	ds_read_b128 v[214:217], v144 offset:4096
	ds_read_b128 v[218:221], v144 offset:5120
	ds_read_b128 v[222:225], v144 offset:6144
	ds_read_b128 v[226:229], v144 offset:7168
	global_load_lds_dwordx4 v[230:231], off
	v_lshl_add_u64 v[230:231], s[22:23], 0, v[138:139]
	s_add_i32 m0, s45, 0xe000
	s_nop 0
	global_load_lds_dwordx4 v[230:231], off
	s_waitcnt vmcnt(16) lgkmcnt(0)
	s_barrier
	v_mfma_f32_16x16x32_bf16 v[126:129], v[146:149], v[184:187], 0
	v_mfma_f32_16x16x32_bf16 v[126:129], v[150:153], v[188:191], v[126:129]
	v_mfma_f32_16x16x32_bf16 v[118:121], v[164:167], v[188:191], 0
	v_mfma_f32_16x16x32_bf16 v[118:121], v[160:163], v[184:187], v[118:121]
	v_mfma_f32_16x16x32_bf16 v[102:105], v[160:163], v[206:209], 0
	v_mfma_f32_16x16x32_bf16 v[102:105], v[164:167], v[210:213], v[102:105]
	v_mfma_f32_16x16x32_bf16 v[110:113], v[150:153], v[210:213], 0
	v_mfma_f32_16x16x32_bf16 v[110:113], v[146:149], v[206:209], v[110:113]
	v_mfma_f32_16x16x32_bf16 v[94:97], v[146:149], v[214:217], 0
	v_mfma_f32_16x16x32_bf16 v[94:97], v[150:153], v[218:221], v[94:97]
	v_mfma_f32_16x16x32_bf16 v[86:89], v[164:167], v[218:221], 0
	v_mfma_f32_16x16x32_bf16 v[86:89], v[160:163], v[214:217], v[86:89]
	v_mfma_f32_16x16x32_bf16 v[70:73], v[160:163], v[222:225], 0
	v_mfma_f32_16x16x32_bf16 v[70:73], v[164:167], v[226:229], v[70:73]
	v_mfma_f32_16x16x32_bf16 v[78:81], v[150:153], v[226:229], 0
	v_mfma_f32_16x16x32_bf16 v[78:81], v[146:149], v[222:225], v[78:81]
	v_mfma_f32_16x16x32_bf16 v[122:125], v[168:171], v[184:187], 0
	v_mfma_f32_16x16x32_bf16 v[122:125], v[172:175], v[188:191], v[122:125]
	v_mfma_f32_16x16x32_bf16 v[114:117], v[180:183], v[188:191], 0
	v_mfma_f32_16x16x32_bf16 v[114:117], v[176:179], v[184:187], v[114:117]
	v_mfma_f32_16x16x32_bf16 v[98:101], v[176:179], v[206:209], 0
	v_mfma_f32_16x16x32_bf16 v[98:101], v[180:183], v[210:213], v[98:101]
	v_mfma_f32_16x16x32_bf16 v[106:109], v[172:175], v[210:213], 0
	v_mfma_f32_16x16x32_bf16 v[106:109], v[168:171], v[206:209], v[106:109]
	v_mfma_f32_16x16x32_bf16 v[90:93], v[168:171], v[214:217], 0
	v_mfma_f32_16x16x32_bf16 v[90:93], v[172:175], v[218:221], v[90:93]
	v_mfma_f32_16x16x32_bf16 v[82:85], v[180:183], v[218:221], 0
	v_mfma_f32_16x16x32_bf16 v[82:85], v[176:179], v[214:217], v[82:85]
	v_mfma_f32_16x16x32_bf16 v[66:69], v[176:179], v[222:225], 0
	v_mfma_f32_16x16x32_bf16 v[66:69], v[180:183], v[226:229], v[66:69]
	v_mfma_f32_16x16x32_bf16 v[74:77], v[172:175], v[226:229], 0
	v_mfma_f32_16x16x32_bf16 v[74:77], v[168:171], v[222:225], v[74:77]
	s_barrier
	s_add_i32 s22, s76, s29
	v_lshl_add_u64 v[230:231], s[40:41], 0, v[0:1]
	s_mov_b32 m0, s22
	ds_read_b128 v[184:187], v144 offset:16384
	ds_read_b128 v[188:191], v144 offset:17408
	ds_read_b128 v[206:209], v144 offset:18432
	ds_read_b128 v[210:213], v144 offset:19456
	ds_read_b128 v[214:217], v144 offset:20480
	ds_read_b128 v[218:221], v144 offset:21504
	ds_read_b128 v[222:225], v144 offset:22528
	ds_read_b128 v[226:229], v144 offset:23552
	global_load_lds_dwordx4 v[230:231], off
	s_add_i32 m0, s22, 0x2000
	s_add_u32 s22, s40, 0x40000
	v_lshl_add_u64 v[232:233], s[40:41], 0, v[130:131]
	s_addc_u32 s23, s41, 0
	s_add_i32 s58, s58, s29
	global_load_lds_dwordx4 v[232:233], off
	v_lshl_add_u64 v[234:235], s[22:23], 0, v[0:1]
	s_mov_b32 m0, s58
	s_nop 0
	global_load_lds_dwordx4 v[234:235], off
	v_lshl_add_u64 v[234:235], s[22:23], 0, v[130:131]
	s_add_i32 m0, s58, 0x2000
	s_nop 0
	global_load_lds_dwordx4 v[234:235], off
	v_lshl_add_u64 v[234:235], s[42:43], 0, v[134:135]
	s_mov_b32 m0, s45
	s_nop 0
	global_load_lds_dwordx4 v[234:235], off
	v_lshl_add_u64 v[234:235], s[42:43], 0, v[132:133]
	s_mov_b32 m0, s46
	s_nop 0
	global_load_lds_dwordx4 v[234:235], off
	s_waitcnt vmcnt(16) lgkmcnt(0)
	s_barrier
; #define PG8_STAGE(bufoff, gbase, voff) do { _Pragma("unroll") for (int _i = 0; _i < 2; ++_i) \
;         __builtin_amdgcn_global_load_lds((const unsigned*)((const char*)(gbase) + (voff)[_i]), (PG8_LAS unsigned*)(lds + (bufoff) + ldsw + _i * 8192), 16, 0, 0); } while (0)
; #define PG8_LDA(dst, b, h) do { _Pragma("unroll") for (int m = 0; m < 4; ++m) _Pragma("unroll") for (int k = 0; k < 2; ++k) dst[m][k] = *(const PG8_LAS bf16x8*)(lds + PG8_SA(b, h) + aoff + m * 2048 + k * 1024); } while (0)
; #define PG8_LDB(dst, b, h) do { _Pragma("unroll") for (int n = 0; n < 2; ++n) _Pragma("unroll") for (int k = 0; k < 2; ++k) dst[n][k] = *(const PG8_LAS bf16x8*)(lds + PG8_SB(b, h) + boff + n * 2048 + k * 1024); } while (0)
; #define PG8_MMA(ai, bj, At, Bt) do { __builtin_amdgcn_s_setprio(1); _Pragma("unroll") for (int m = 0; m < 4; ++m) _Pragma("unroll") for (int n = 0; n < 2; ++n) _Pragma("unroll") for (int k = 0; k < 2; ++k) \
;         acc[ai][bj][m][n] = __builtin_amdgcn_mfma_f32_16x16x32_bf16(Bt[n][k], At[m][k], acc[ai][bj][m][n], 0, 0, 0); __builtin_amdgcn_s_setprio(0); } while (0)
; #define PG8_WAIT_V(n) asm volatile("s_waitcnt vmcnt(" #n ")" ::: "memory")
; #define PG8_WAIT_L(n) asm volatile("s_waitcnt lgkmcnt(" #n ")" ::: "memory")
; #define PG8_BAR __builtin_amdgcn_s_barrier()
; #define PG8_SCHED __builtin_amdgcn_sched_barrier(0)
; template <class Epi, class Sched, bool ALIGN_EPI = false, bool SP2 = false>
; __device__ __forceinline__ void gemm_phase(PG8_LAS unsigned char* lds, const Gemm g, const Sched& S, const Epi& E) {
;     ...
;             PG8_WAIT_V(8); PG8_WAIT_L(0); PG8_BAR; PG8_MMA(1, 0, At, B0); PG8_MMA(1, 1, At, B1); PG8_BAR; PG8_SCHED;
;             PG8_LDB(B0, 1, 0); PG8_LDB(B1, 1, 1); PG8_SCHED; PG8_LDA(At, 1, 0); PG8_STAGE(PG8_SA(0, 1), a2 + hstep, voffA);
;             PG8_WAIT_V(8); PG8_WAIT_L(0); PG8_BAR; PG8_MMA(0, 0, At, B0); PG8_MMA(0, 1, At, B1); PG8_BAR; PG8_SCHED;
	v_mfma_f32_16x16x32_bf16 v[62:65], v[146:149], v[184:187], 0
	v_mfma_f32_16x16x32_bf16 v[62:65], v[150:153], v[188:191], v[62:65]
	v_mfma_f32_16x16x32_bf16 v[54:57], v[164:167], v[188:191], 0
	v_mfma_f32_16x16x32_bf16 v[54:57], v[160:163], v[184:187], v[54:57]
	v_mfma_f32_16x16x32_bf16 v[38:41], v[160:163], v[206:209], 0
	v_mfma_f32_16x16x32_bf16 v[38:41], v[164:167], v[210:213], v[38:41]
	v_mfma_f32_16x16x32_bf16 v[46:49], v[150:153], v[210:213], 0
	v_mfma_f32_16x16x32_bf16 v[46:49], v[146:149], v[206:209], v[46:49]
	v_mfma_f32_16x16x32_bf16 v[30:33], v[146:149], v[214:217], 0
	v_mfma_f32_16x16x32_bf16 v[30:33], v[150:153], v[218:221], v[30:33]
	v_mfma_f32_16x16x32_bf16 v[22:25], v[164:167], v[218:221], 0
	v_mfma_f32_16x16x32_bf16 v[22:25], v[160:163], v[214:217], v[22:25]
	v_mfma_f32_16x16x32_bf16 v[6:9], v[160:163], v[222:225], 0
	v_mfma_f32_16x16x32_bf16 v[6:9], v[164:167], v[226:229], v[6:9]
	v_mfma_f32_16x16x32_bf16 v[14:17], v[150:153], v[226:229], 0
	v_mfma_f32_16x16x32_bf16 v[14:17], v[146:149], v[222:225], v[14:17]
	v_mfma_f32_16x16x32_bf16 v[58:61], v[168:171], v[184:187], 0
	v_mfma_f32_16x16x32_bf16 v[58:61], v[172:175], v[188:191], v[58:61]
	v_mfma_f32_16x16x32_bf16 v[50:53], v[180:183], v[188:191], 0
	v_mfma_f32_16x16x32_bf16 v[50:53], v[176:179], v[184:187], v[50:53]
	v_mfma_f32_16x16x32_bf16 v[34:37], v[176:179], v[206:209], 0
	v_mfma_f32_16x16x32_bf16 v[34:37], v[180:183], v[210:213], v[34:37]
	v_mfma_f32_16x16x32_bf16 v[42:45], v[172:175], v[210:213], 0
	v_mfma_f32_16x16x32_bf16 v[42:45], v[168:171], v[206:209], v[42:45]
	v_mfma_f32_16x16x32_bf16 v[26:29], v[168:171], v[214:217], 0
	v_mfma_f32_16x16x32_bf16 v[26:29], v[172:175], v[218:221], v[26:29]
	v_mfma_f32_16x16x32_bf16 v[18:21], v[180:183], v[218:221], 0
	v_mfma_f32_16x16x32_bf16 v[18:21], v[176:179], v[214:217], v[18:21]
	v_mfma_f32_16x16x32_bf16 v[2:5], v[176:179], v[222:225], 0
	v_mfma_f32_16x16x32_bf16 v[2:5], v[180:183], v[226:229], v[2:5]
	v_mfma_f32_16x16x32_bf16 v[10:13], v[172:175], v[226:229], 0
	v_mfma_f32_16x16x32_bf16 v[10:13], v[168:171], v[222:225], v[10:13]
	s_barrier
	s_add_i32 s58, 0, 0x18000
	v_add_u32_e32 v145, s58, v142
	s_add_i32 s59, 0, 0x1c000
	ds_read_b128 v[146:149], v145
	ds_read_b128 v[150:153], v145 offset:1024
	ds_read_b128 v[160:163], v145 offset:2048
	ds_read_b128 v[164:167], v145 offset:3072
	v_add_u32_e32 v145, s59, v142
	ds_read_b128 v[168:171], v145
	ds_read_b128 v[172:175], v145 offset:1024
	ds_read_b128 v[176:179], v145 offset:2048
	ds_read_b128 v[180:183], v145 offset:3072
	s_add_u32 s22, s42, 0x40000
	s_addc_u32 s23, s43, 0
	s_mov_b32 m0, s47
	v_lshl_add_u64 v[234:235], s[22:23], 0, v[134:135]
	ds_read_b128 v[184:187], v144 offset:32768
	ds_read_b128 v[188:191], v144 offset:33792
	ds_read_b128 v[206:209], v144 offset:34816
	ds_read_b128 v[210:213], v144 offset:35840
	ds_read_b128 v[214:217], v144 offset:36864
	ds_read_b128 v[218:221], v144 offset:37888
	ds_read_b128 v[222:225], v144 offset:38912
	ds_read_b128 v[226:229], v144 offset:39936
	global_load_lds_dwordx4 v[234:235], off
	v_lshl_add_u64 v[234:235], s[22:23], 0, v[132:133]
	s_mov_b32 m0, s48
	s_nop 0
	global_load_lds_dwordx4 v[234:235], off
	s_waitcnt vmcnt(8) lgkmcnt(0)
	s_barrier
	v_mfma_f32_16x16x32_bf16 v[126:129], v[146:149], v[184:187], v[126:129]
	v_mfma_f32_16x16x32_bf16 v[126:129], v[150:153], v[188:191], v[126:129]
	v_mfma_f32_16x16x32_bf16 v[118:121], v[164:167], v[188:191], v[118:121]
	v_mfma_f32_16x16x32_bf16 v[118:121], v[160:163], v[184:187], v[118:121]
	v_mfma_f32_16x16x32_bf16 v[102:105], v[160:163], v[206:209], v[102:105]
	v_mfma_f32_16x16x32_bf16 v[102:105], v[164:167], v[210:213], v[102:105]
	v_mfma_f32_16x16x32_bf16 v[110:113], v[150:153], v[210:213], v[110:113]
	v_mfma_f32_16x16x32_bf16 v[110:113], v[146:149], v[206:209], v[110:113]
	v_mfma_f32_16x16x32_bf16 v[94:97], v[146:149], v[214:217], v[94:97]
	v_mfma_f32_16x16x32_bf16 v[94:97], v[150:153], v[218:221], v[94:97]
	v_mfma_f32_16x16x32_bf16 v[86:89], v[164:167], v[218:221], v[86:89]
	v_mfma_f32_16x16x32_bf16 v[86:89], v[160:163], v[214:217], v[86:89]
	v_mfma_f32_16x16x32_bf16 v[70:73], v[160:163], v[222:225], v[70:73]
	v_mfma_f32_16x16x32_bf16 v[70:73], v[164:167], v[226:229], v[70:73]
	v_mfma_f32_16x16x32_bf16 v[78:81], v[150:153], v[226:229], v[78:81]
	v_mfma_f32_16x16x32_bf16 v[78:81], v[146:149], v[222:225], v[78:81]
	v_mfma_f32_16x16x32_bf16 v[122:125], v[168:171], v[184:187], v[122:125]
	v_mfma_f32_16x16x32_bf16 v[122:125], v[172:175], v[188:191], v[122:125]
	v_mfma_f32_16x16x32_bf16 v[114:117], v[180:183], v[188:191], v[114:117]
	v_mfma_f32_16x16x32_bf16 v[114:117], v[176:179], v[184:187], v[114:117]
	v_mfma_f32_16x16x32_bf16 v[98:101], v[176:179], v[206:209], v[98:101]
	v_mfma_f32_16x16x32_bf16 v[98:101], v[180:183], v[210:213], v[98:101]
	v_mfma_f32_16x16x32_bf16 v[106:109], v[172:175], v[210:213], v[106:109]
	v_mfma_f32_16x16x32_bf16 v[106:109], v[168:171], v[206:209], v[106:109]
	v_mfma_f32_16x16x32_bf16 v[90:93], v[168:171], v[214:217], v[90:93]
	v_mfma_f32_16x16x32_bf16 v[90:93], v[172:175], v[218:221], v[90:93]
	v_mfma_f32_16x16x32_bf16 v[82:85], v[180:183], v[218:221], v[82:85]
	v_mfma_f32_16x16x32_bf16 v[82:85], v[176:179], v[214:217], v[82:85]
	v_mfma_f32_16x16x32_bf16 v[66:69], v[176:179], v[222:225], v[66:69]
	v_mfma_f32_16x16x32_bf16 v[66:69], v[180:183], v[226:229], v[66:69]
	v_mfma_f32_16x16x32_bf16 v[74:77], v[172:175], v[226:229], v[74:77]
	v_mfma_f32_16x16x32_bf16 v[74:77], v[168:171], v[222:225], v[74:77]
	s_barrier
; #define PG8_STAGE(bufoff, gbase, voff) do { _Pragma("unroll") for (int _i = 0; _i < 2; ++_i) \
;         __builtin_amdgcn_global_load_lds((const unsigned*)((const char*)(gbase) + (voff)[_i]), (PG8_LAS unsigned*)(lds + (bufoff) + ldsw + _i * 8192), 16, 0, 0); } while (0)
; #define PG8_LDA(dst, b, h) do { _Pragma("unroll") for (int m = 0; m < 4; ++m) _Pragma("unroll") for (int k = 0; k < 2; ++k) dst[m][k] = *(const PG8_LAS bf16x8*)(lds + PG8_SA(b, h) + aoff + m * 2048 + k * 1024); } while (0)
; #define PG8_LDB(dst, b, h) do { _Pragma("unroll") for (int n = 0; n < 2; ++n) _Pragma("unroll") for (int k = 0; k < 2; ++k) dst[n][k] = *(const PG8_LAS bf16x8*)(lds + PG8_SB(b, h) + boff + n * 2048 + k * 1024); } while (0)
; #define PG8_MMA(ai, bj, At, Bt) do { __builtin_amdgcn_s_setprio(1); _Pragma("unroll") for (int m = 0; m < 4; ++m) _Pragma("unroll") for (int n = 0; n < 2; ++n) _Pragma("unroll") for (int k = 0; k < 2; ++k) \
;         acc[ai][bj][m][n] = __builtin_amdgcn_mfma_f32_16x16x32_bf16(Bt[n][k], At[m][k], acc[ai][bj][m][n], 0, 0, 0); __builtin_amdgcn_s_setprio(0); } while (0)
; #define PG8_WAIT_V(n) asm volatile("s_waitcnt vmcnt(" #n ")" ::: "memory")
; #define PG8_BAR __builtin_amdgcn_s_barrier()
; template <class Epi, class Sched, bool ALIGN_EPI = false, bool SP2 = false>
; __device__ __forceinline__ void gemm_phase(PG8_LAS unsigned char* lds, const Gemm g, const Sched& S, const Epi& E) {
;     ...
;         for (int t = 0; t < nt; t += 2) {
;             const bool last = (t == nt - 2);
;             const char* a1 = cA + (size_t)(t + 1) * kstepA;
;             const char* a2 = last ? nA : cA + (size_t)(t + 2) * kstepA; const char* b2 = last ? nB : cB + (size_t)(t + 2) * kstep;
;             const char* a3 = a2 + kstepA; const char* b3 = b2 + kstep;
;             if (last && has_next) S.a_ready(nxt);
;             if constexpr (SP2) {
;             PG8_LDB(B0, 0, 0); PG8_LDB(B1, 0, 1); PG8_SCHED; PG8_LDA(At, 0, 0); PG8_STAGE(PG8_SA(1, 1), a1 + hstep, voffA);
;             PG8_WAIT_V(8); PG8_WAIT_L(0); PG8_BAR; PG8_MMA(0, 0, At, B0); PG8_MMA(0, 1, At, B1); PG8_BAR; PG8_SCHED;
;     ...
;             PG8_LDA(At, 1, 1); PG8_STAGE(PG8_SB(1, 0), b3, voffB); PG8_STAGE(PG8_SB(1, 1), b3 + hstep, voffB); PG8_STAGE(PG8_SA(1, 0), a3, voffA);
;             PG8_WAIT_V(8); PG8_WAIT_L(0); PG8_BAR; PG8_MMA(1, 0, At, B0); PG8_MMA(1, 1, At, B1); PG8_BAR; PG8_SCHED;
	s_add_i32 s22, s58, s29
	v_lshl_add_u64 v[230:231], v[230:231], 0, s[38:39]
	s_mov_b32 m0, s22
	ds_read_b128 v[184:187], v144 offset:49152
	ds_read_b128 v[188:191], v144 offset:50176
	ds_read_b128 v[206:209], v144 offset:51200
	ds_read_b128 v[210:213], v144 offset:52224
	ds_read_b128 v[214:217], v144 offset:53248
	ds_read_b128 v[218:221], v144 offset:54272
	ds_read_b128 v[222:225], v144 offset:55296
	ds_read_b128 v[226:229], v144 offset:56320
	global_load_lds_dwordx4 v[230:231], off
	s_add_i32 m0, s22, 0x2000
	s_add_u32 s22, s40, 0x40080
	v_lshl_add_u64 v[230:231], v[232:233], 0, s[38:39]
	s_addc_u32 s23, s41, 0
	s_add_i32 s40, s59, s29
	global_load_lds_dwordx4 v[230:231], off
	v_lshl_add_u64 v[230:231], s[22:23], 0, v[0:1]
	s_mov_b32 m0, s40
	s_nop 0
	global_load_lds_dwordx4 v[230:231], off
	v_lshl_add_u64 v[230:231], s[22:23], 0, v[130:131]
	s_add_i32 m0, s40, 0x2000
	s_nop 0
	global_load_lds_dwordx4 v[230:231], off
	v_lshl_add_u64 v[230:231], s[26:27], 0, v[134:135]
	s_mov_b32 m0, s49
	s_nop 0
	global_load_lds_dwordx4 v[230:231], off
	v_lshl_add_u64 v[230:231], s[26:27], 0, v[132:133]
	s_mov_b32 m0, s50
	s_nop 0
	global_load_lds_dwordx4 v[230:231], off
	s_waitcnt vmcnt(8) lgkmcnt(0)
	s_barrier
	v_mfma_f32_16x16x32_bf16 v[62:65], v[146:149], v[184:187], v[62:65]
	v_mfma_f32_16x16x32_bf16 v[62:65], v[150:153], v[188:191], v[62:65]
	v_mfma_f32_16x16x32_bf16 v[54:57], v[164:167], v[188:191], v[54:57]
	v_mfma_f32_16x16x32_bf16 v[54:57], v[160:163], v[184:187], v[54:57]
	v_mfma_f32_16x16x32_bf16 v[38:41], v[160:163], v[206:209], v[38:41]
	v_mfma_f32_16x16x32_bf16 v[38:41], v[164:167], v[210:213], v[38:41]
	v_mfma_f32_16x16x32_bf16 v[46:49], v[150:153], v[210:213], v[46:49]
	v_mfma_f32_16x16x32_bf16 v[46:49], v[146:149], v[206:209], v[46:49]
	v_mfma_f32_16x16x32_bf16 v[30:33], v[146:149], v[214:217], v[30:33]
	v_mfma_f32_16x16x32_bf16 v[30:33], v[150:153], v[218:221], v[30:33]
	v_mfma_f32_16x16x32_bf16 v[22:25], v[164:167], v[218:221], v[22:25]
	v_mfma_f32_16x16x32_bf16 v[22:25], v[160:163], v[214:217], v[22:25]
	v_mfma_f32_16x16x32_bf16 v[6:9], v[160:163], v[222:225], v[6:9]
	v_mfma_f32_16x16x32_bf16 v[6:9], v[164:167], v[226:229], v[6:9]
	v_mfma_f32_16x16x32_bf16 v[14:17], v[150:153], v[226:229], v[14:17]
	v_mfma_f32_16x16x32_bf16 v[14:17], v[146:149], v[222:225], v[14:17]
	v_mfma_f32_16x16x32_bf16 v[58:61], v[168:171], v[184:187], v[58:61]
	v_mfma_f32_16x16x32_bf16 v[58:61], v[172:175], v[188:191], v[58:61]
	v_mfma_f32_16x16x32_bf16 v[50:53], v[180:183], v[188:191], v[50:53]
	v_mfma_f32_16x16x32_bf16 v[50:53], v[176:179], v[184:187], v[50:53]
	v_mfma_f32_16x16x32_bf16 v[34:37], v[176:179], v[206:209], v[34:37]
	v_mfma_f32_16x16x32_bf16 v[34:37], v[180:183], v[210:213], v[34:37]
	v_mfma_f32_16x16x32_bf16 v[42:45], v[172:175], v[210:213], v[42:45]
	v_mfma_f32_16x16x32_bf16 v[42:45], v[168:171], v[206:209], v[42:45]
	v_mfma_f32_16x16x32_bf16 v[26:29], v[168:171], v[214:217], v[26:29]
	v_mfma_f32_16x16x32_bf16 v[26:29], v[172:175], v[218:221], v[26:29]
	v_mfma_f32_16x16x32_bf16 v[18:21], v[180:183], v[218:221], v[18:21]
	v_mfma_f32_16x16x32_bf16 v[18:21], v[176:179], v[214:217], v[18:21]
	v_mfma_f32_16x16x32_bf16 v[2:5], v[176:179], v[222:225], v[2:5]
	v_mfma_f32_16x16x32_bf16 v[2:5], v[180:183], v[226:229], v[2:5]
	v_mfma_f32_16x16x32_bf16 v[10:13], v[172:175], v[226:229], v[10:13]
	v_mfma_f32_16x16x32_bf16 v[10:13], v[168:171], v[222:225], v[10:13]
	s_barrier
	s_add_i32 s57, s57, 2
	s_add_u32 s55, s55, 0x100
	s_addc_u32 s56, s56, 0
	s_cmp_gt_u32 s57, 13
	s_mov_b64 s[22:23], s[24:25]
	s_cbranch_scc1 .Lpeel_exit_2
.LBB0_409:
	s_add_u32 s24, s22, 0x8000
	s_addc_u32 s25, s23, 0
	s_cmp_eq_u32 s57, 12
	s_cselect_b32 s42, s53, s24
	s_cselect_b32 s43, s11, s25
	s_cselect_b32 s40, s54, s55
	s_cselect_b32 s41, s9, s56
	s_add_u32 s26, s42, 0x4000
	s_addc_u32 s27, s43, 0
	v_add_u32_e32 v145, s76, v142
	s_add_i32 s58, 0, 0x14000
	ds_read_b128 v[146:149], v145
	ds_read_b128 v[150:153], v145 offset:1024
	ds_read_b128 v[160:163], v145 offset:2048
	ds_read_b128 v[164:167], v145 offset:3072
	v_add_u32_e32 v145, s58, v142
	ds_read_b128 v[168:171], v145
	ds_read_b128 v[172:175], v145 offset:1024
	ds_read_b128 v[176:179], v145 offset:2048
	ds_read_b128 v[180:183], v145 offset:3072
	v_lshl_add_u64 v[230:231], s[22:23], 0, v[140:141]
	s_add_i32 m0, s45, 0xc000
	ds_read_b128 v[184:187], v144
	ds_read_b128 v[188:191], v144 offset:1024
	ds_read_b128 v[206:209], v144 offset:2048
	ds_read_b128 v[210:213], v144 offset:3072
	ds_read_b128 v[214:217], v144 offset:4096
	ds_read_b128 v[218:221], v144 offset:5120
	ds_read_b128 v[222:225], v144 offset:6144
	ds_read_b128 v[226:229], v144 offset:7168
	global_load_lds_dwordx4 v[230:231], off
	v_lshl_add_u64 v[230:231], s[22:23], 0, v[138:139]
	s_add_i32 m0, s45, 0xe000
	s_nop 0
	global_load_lds_dwordx4 v[230:231], off
	s_waitcnt vmcnt(8) lgkmcnt(0)
	s_barrier
; #define PG8_STAGE(bufoff, gbase, voff) do { _Pragma("unroll") for (int _i = 0; _i < 2; ++_i) \
;         __builtin_amdgcn_global_load_lds((const unsigned*)((const char*)(gbase) + (voff)[_i]), (PG8_LAS unsigned*)(lds + (bufoff) + ldsw + _i * 8192), 16, 0, 0); } while (0)
; #define PG8_LDA(dst, b, h) do { _Pragma("unroll") for (int m = 0; m < 4; ++m) _Pragma("unroll") for (int k = 0; k < 2; ++k) dst[m][k] = *(const PG8_LAS bf16x8*)(lds + PG8_SA(b, h) + aoff + m * 2048 + k * 1024); } while (0)
; #define PG8_MMA(ai, bj, At, Bt) do { __builtin_amdgcn_s_setprio(1); _Pragma("unroll") for (int m = 0; m < 4; ++m) _Pragma("unroll") for (int n = 0; n < 2; ++n) _Pragma("unroll") for (int k = 0; k < 2; ++k) \
;         acc[ai][bj][m][n] = __builtin_amdgcn_mfma_f32_16x16x32_bf16(Bt[n][k], At[m][k], acc[ai][bj][m][n], 0, 0, 0); __builtin_amdgcn_s_setprio(0); } while (0)
; #define PG8_WAIT_V(n) asm volatile("s_waitcnt vmcnt(" #n ")" ::: "memory")
; #define PG8_WAIT_L(n) asm volatile("s_waitcnt lgkmcnt(" #n ")" ::: "memory")
; #define PG8_BAR __builtin_amdgcn_s_barrier()
; #define PG8_SCHED __builtin_amdgcn_sched_barrier(0)
; template <class Epi, class Sched, bool ALIGN_EPI = false, bool SP2 = false>
; __device__ __forceinline__ void gemm_phase(PG8_LAS unsigned char* lds, const Gemm g, const Sched& S, const Epi& E) {
;     ...
;             PG8_WAIT_V(8); PG8_WAIT_L(0); PG8_BAR; PG8_MMA(0, 0, At, B0); PG8_MMA(0, 1, At, B1); PG8_BAR; PG8_SCHED;
;             PG8_LDA(At, 0, 1); PG8_STAGE(PG8_SB(0, 0), b2, voffB); PG8_STAGE(PG8_SB(0, 1), b2 + hstep, voffB); PG8_STAGE(PG8_SA(0, 0), a2, voffA);
;             PG8_WAIT_V(8); PG8_WAIT_L(0); PG8_BAR; PG8_MMA(1, 0, At, B0); PG8_MMA(1, 1, At, B1); PG8_BAR; PG8_SCHED;
	v_mfma_f32_16x16x32_bf16 v[126:129], v[146:149], v[184:187], v[126:129]
	v_mfma_f32_16x16x32_bf16 v[126:129], v[150:153], v[188:191], v[126:129]
	v_mfma_f32_16x16x32_bf16 v[118:121], v[164:167], v[188:191], v[118:121]
	v_mfma_f32_16x16x32_bf16 v[118:121], v[160:163], v[184:187], v[118:121]
	v_mfma_f32_16x16x32_bf16 v[102:105], v[160:163], v[206:209], v[102:105]
	v_mfma_f32_16x16x32_bf16 v[102:105], v[164:167], v[210:213], v[102:105]
	v_mfma_f32_16x16x32_bf16 v[110:113], v[150:153], v[210:213], v[110:113]
	v_mfma_f32_16x16x32_bf16 v[110:113], v[146:149], v[206:209], v[110:113]
	v_mfma_f32_16x16x32_bf16 v[94:97], v[146:149], v[214:217], v[94:97]
	v_mfma_f32_16x16x32_bf16 v[94:97], v[150:153], v[218:221], v[94:97]
	v_mfma_f32_16x16x32_bf16 v[86:89], v[164:167], v[218:221], v[86:89]
	v_mfma_f32_16x16x32_bf16 v[86:89], v[160:163], v[214:217], v[86:89]
	v_mfma_f32_16x16x32_bf16 v[70:73], v[160:163], v[222:225], v[70:73]
	v_mfma_f32_16x16x32_bf16 v[70:73], v[164:167], v[226:229], v[70:73]
	v_mfma_f32_16x16x32_bf16 v[78:81], v[150:153], v[226:229], v[78:81]
	v_mfma_f32_16x16x32_bf16 v[78:81], v[146:149], v[222:225], v[78:81]
	v_mfma_f32_16x16x32_bf16 v[122:125], v[168:171], v[184:187], v[122:125]
	v_mfma_f32_16x16x32_bf16 v[122:125], v[172:175], v[188:191], v[122:125]
	v_mfma_f32_16x16x32_bf16 v[114:117], v[180:183], v[188:191], v[114:117]
	v_mfma_f32_16x16x32_bf16 v[114:117], v[176:179], v[184:187], v[114:117]
	v_mfma_f32_16x16x32_bf16 v[98:101], v[176:179], v[206:209], v[98:101]
	v_mfma_f32_16x16x32_bf16 v[98:101], v[180:183], v[210:213], v[98:101]
	v_mfma_f32_16x16x32_bf16 v[106:109], v[172:175], v[210:213], v[106:109]
	v_mfma_f32_16x16x32_bf16 v[106:109], v[168:171], v[206:209], v[106:109]
	v_mfma_f32_16x16x32_bf16 v[90:93], v[168:171], v[214:217], v[90:93]
	v_mfma_f32_16x16x32_bf16 v[90:93], v[172:175], v[218:221], v[90:93]
	v_mfma_f32_16x16x32_bf16 v[82:85], v[180:183], v[218:221], v[82:85]
	v_mfma_f32_16x16x32_bf16 v[82:85], v[176:179], v[214:217], v[82:85]
	v_mfma_f32_16x16x32_bf16 v[66:69], v[176:179], v[222:225], v[66:69]
	v_mfma_f32_16x16x32_bf16 v[66:69], v[180:183], v[226:229], v[66:69]
	v_mfma_f32_16x16x32_bf16 v[74:77], v[172:175], v[226:229], v[74:77]
	v_mfma_f32_16x16x32_bf16 v[74:77], v[168:171], v[222:225], v[74:77]
	s_barrier
	s_add_i32 s22, s76, s29
	v_lshl_add_u64 v[230:231], s[40:41], 0, v[0:1]
	s_mov_b32 m0, s22
	ds_read_b128 v[184:187], v144 offset:16384
	ds_read_b128 v[188:191], v144 offset:17408
	ds_read_b128 v[206:209], v144 offset:18432
	ds_read_b128 v[210:213], v144 offset:19456
	ds_read_b128 v[214:217], v144 offset:20480
	ds_read_b128 v[218:221], v144 offset:21504
	ds_read_b128 v[222:225], v144 offset:22528
	ds_read_b128 v[226:229], v144 offset:23552
	global_load_lds_dwordx4 v[230:231], off
	s_add_i32 m0, s22, 0x2000
	s_add_u32 s22, s40, 0x40000
	v_lshl_add_u64 v[232:233], s[40:41], 0, v[130:131]
	s_addc_u32 s23, s41, 0
	s_add_i32 s58, s58, s29
	global_load_lds_dwordx4 v[232:233], off
	v_lshl_add_u64 v[234:235], s[22:23], 0, v[0:1]
	s_mov_b32 m0, s58
	s_nop 0
	global_load_lds_dwordx4 v[234:235], off
	v_lshl_add_u64 v[234:235], s[22:23], 0, v[130:131]
	s_add_i32 m0, s58, 0x2000
	s_nop 0
	global_load_lds_dwordx4 v[234:235], off
	v_lshl_add_u64 v[234:235], s[42:43], 0, v[134:135]
	s_mov_b32 m0, s45
	s_nop 0
	global_load_lds_dwordx4 v[234:235], off
	v_lshl_add_u64 v[234:235], s[42:43], 0, v[132:133]
	s_mov_b32 m0, s46
	s_nop 0
	global_load_lds_dwordx4 v[234:235], off
	s_waitcnt vmcnt(8) lgkmcnt(0)
	s_barrier
	v_mfma_f32_16x16x32_bf16 v[62:65], v[146:149], v[184:187], v[62:65]
	v_mfma_f32_16x16x32_bf16 v[62:65], v[150:153], v[188:191], v[62:65]
	v_mfma_f32_16x16x32_bf16 v[54:57], v[164:167], v[188:191], v[54:57]
	v_mfma_f32_16x16x32_bf16 v[54:57], v[160:163], v[184:187], v[54:57]
	v_mfma_f32_16x16x32_bf16 v[38:41], v[160:163], v[206:209], v[38:41]
	v_mfma_f32_16x16x32_bf16 v[38:41], v[164:167], v[210:213], v[38:41]
	v_mfma_f32_16x16x32_bf16 v[46:49], v[150:153], v[210:213], v[46:49]
	v_mfma_f32_16x16x32_bf16 v[46:49], v[146:149], v[206:209], v[46:49]
	v_mfma_f32_16x16x32_bf16 v[30:33], v[146:149], v[214:217], v[30:33]
	v_mfma_f32_16x16x32_bf16 v[30:33], v[150:153], v[218:221], v[30:33]
	v_mfma_f32_16x16x32_bf16 v[22:25], v[164:167], v[218:221], v[22:25]
	v_mfma_f32_16x16x32_bf16 v[22:25], v[160:163], v[214:217], v[22:25]
	v_mfma_f32_16x16x32_bf16 v[6:9], v[160:163], v[222:225], v[6:9]
	v_mfma_f32_16x16x32_bf16 v[6:9], v[164:167], v[226:229], v[6:9]
	v_mfma_f32_16x16x32_bf16 v[14:17], v[150:153], v[226:229], v[14:17]
	v_mfma_f32_16x16x32_bf16 v[14:17], v[146:149], v[222:225], v[14:17]
	v_mfma_f32_16x16x32_bf16 v[58:61], v[168:171], v[184:187], v[58:61]
	v_mfma_f32_16x16x32_bf16 v[58:61], v[172:175], v[188:191], v[58:61]
	v_mfma_f32_16x16x32_bf16 v[50:53], v[180:183], v[188:191], v[50:53]
	v_mfma_f32_16x16x32_bf16 v[50:53], v[176:179], v[184:187], v[50:53]
	v_mfma_f32_16x16x32_bf16 v[34:37], v[176:179], v[206:209], v[34:37]
	v_mfma_f32_16x16x32_bf16 v[34:37], v[180:183], v[210:213], v[34:37]
	v_mfma_f32_16x16x32_bf16 v[42:45], v[172:175], v[210:213], v[42:45]
	v_mfma_f32_16x16x32_bf16 v[42:45], v[168:171], v[206:209], v[42:45]
	v_mfma_f32_16x16x32_bf16 v[26:29], v[168:171], v[214:217], v[26:29]
	v_mfma_f32_16x16x32_bf16 v[26:29], v[172:175], v[218:221], v[26:29]
	v_mfma_f32_16x16x32_bf16 v[18:21], v[180:183], v[218:221], v[18:21]
	v_mfma_f32_16x16x32_bf16 v[18:21], v[176:179], v[214:217], v[18:21]
	v_mfma_f32_16x16x32_bf16 v[2:5], v[176:179], v[222:225], v[2:5]
	v_mfma_f32_16x16x32_bf16 v[2:5], v[180:183], v[226:229], v[2:5]
	v_mfma_f32_16x16x32_bf16 v[10:13], v[172:175], v[226:229], v[10:13]
	v_mfma_f32_16x16x32_bf16 v[10:13], v[168:171], v[222:225], v[10:13]
	s_barrier
; #define PG8_STAGE(bufoff, gbase, voff) do { _Pragma("unroll") for (int _i = 0; _i < 2; ++_i) \
;         __builtin_amdgcn_global_load_lds((const unsigned*)((const char*)(gbase) + (voff)[_i]), (PG8_LAS unsigned*)(lds + (bufoff) + ldsw + _i * 8192), 16, 0, 0); } while (0)
; #define PG8_LDA(dst, b, h) do { _Pragma("unroll") for (int m = 0; m < 4; ++m) _Pragma("unroll") for (int k = 0; k < 2; ++k) dst[m][k] = *(const PG8_LAS bf16x8*)(lds + PG8_SA(b, h) + aoff + m * 2048 + k * 1024); } while (0)
; #define PG8_LDB(dst, b, h) do { _Pragma("unroll") for (int n = 0; n < 2; ++n) _Pragma("unroll") for (int k = 0; k < 2; ++k) dst[n][k] = *(const PG8_LAS bf16x8*)(lds + PG8_SB(b, h) + boff + n * 2048 + k * 1024); } while (0)
; #define PG8_MMA(ai, bj, At, Bt) do { __builtin_amdgcn_s_setprio(1); _Pragma("unroll") for (int m = 0; m < 4; ++m) _Pragma("unroll") for (int n = 0; n < 2; ++n) _Pragma("unroll") for (int k = 0; k < 2; ++k) \
;         acc[ai][bj][m][n] = __builtin_amdgcn_mfma_f32_16x16x32_bf16(Bt[n][k], At[m][k], acc[ai][bj][m][n], 0, 0, 0); __builtin_amdgcn_s_setprio(0); } while (0)
; #define PG8_WAIT_V(n) asm volatile("s_waitcnt vmcnt(" #n ")" ::: "memory")
; #define PG8_WAIT_L(n) asm volatile("s_waitcnt lgkmcnt(" #n ")" ::: "memory")
; #define PG8_BAR __builtin_amdgcn_s_barrier()
; #define PG8_SCHED __builtin_amdgcn_sched_barrier(0)
; template <class Epi, class Sched, bool ALIGN_EPI = false, bool SP2 = false>
; __device__ __forceinline__ void gemm_phase(PG8_LAS unsigned char* lds, const Gemm g, const Sched& S, const Epi& E) {
;     ...
;             PG8_LDB(B0, 1, 0); PG8_LDB(B1, 1, 1); PG8_SCHED; PG8_LDA(At, 1, 0); PG8_STAGE(PG8_SA(0, 1), a2 + hstep, voffA);
;             PG8_WAIT_V(8); PG8_WAIT_L(0); PG8_BAR; PG8_MMA(0, 0, At, B0); PG8_MMA(0, 1, At, B1); PG8_BAR; PG8_SCHED;
;             PG8_LDA(At, 1, 1); PG8_STAGE(PG8_SB(1, 0), b3, voffB); PG8_STAGE(PG8_SB(1, 1), b3 + hstep, voffB); PG8_STAGE(PG8_SA(1, 0), a3, voffA);
;             PG8_WAIT_V(8); PG8_WAIT_L(0); PG8_BAR; PG8_MMA(1, 0, At, B0); PG8_MMA(1, 1, At, B1); PG8_BAR; PG8_SCHED;
	s_add_i32 s58, 0, 0x18000
	v_add_u32_e32 v145, s58, v142
	s_add_i32 s59, 0, 0x1c000
	ds_read_b128 v[146:149], v145
	ds_read_b128 v[150:153], v145 offset:1024
	ds_read_b128 v[160:163], v145 offset:2048
	ds_read_b128 v[164:167], v145 offset:3072
	v_add_u32_e32 v145, s59, v142
	ds_read_b128 v[168:171], v145
	ds_read_b128 v[172:175], v145 offset:1024
	ds_read_b128 v[176:179], v145 offset:2048
	ds_read_b128 v[180:183], v145 offset:3072
	s_add_u32 s22, s42, 0x40000
	s_addc_u32 s23, s43, 0
	s_mov_b32 m0, s47
	v_lshl_add_u64 v[234:235], s[22:23], 0, v[134:135]
	ds_read_b128 v[184:187], v144 offset:32768
	ds_read_b128 v[188:191], v144 offset:33792
	ds_read_b128 v[206:209], v144 offset:34816
	ds_read_b128 v[210:213], v144 offset:35840
	ds_read_b128 v[214:217], v144 offset:36864
	ds_read_b128 v[218:221], v144 offset:37888
	ds_read_b128 v[222:225], v144 offset:38912
	ds_read_b128 v[226:229], v144 offset:39936
	global_load_lds_dwordx4 v[234:235], off
	v_lshl_add_u64 v[234:235], s[22:23], 0, v[132:133]
	s_mov_b32 m0, s48
	s_nop 0
	global_load_lds_dwordx4 v[234:235], off
	s_waitcnt vmcnt(8) lgkmcnt(0)
	s_barrier
	v_mfma_f32_16x16x32_bf16 v[126:129], v[146:149], v[184:187], v[126:129]
	v_mfma_f32_16x16x32_bf16 v[126:129], v[150:153], v[188:191], v[126:129]
	v_mfma_f32_16x16x32_bf16 v[118:121], v[164:167], v[188:191], v[118:121]
	v_mfma_f32_16x16x32_bf16 v[118:121], v[160:163], v[184:187], v[118:121]
	v_mfma_f32_16x16x32_bf16 v[102:105], v[160:163], v[206:209], v[102:105]
	v_mfma_f32_16x16x32_bf16 v[102:105], v[164:167], v[210:213], v[102:105]
	v_mfma_f32_16x16x32_bf16 v[110:113], v[150:153], v[210:213], v[110:113]
	v_mfma_f32_16x16x32_bf16 v[110:113], v[146:149], v[206:209], v[110:113]
	v_mfma_f32_16x16x32_bf16 v[94:97], v[146:149], v[214:217], v[94:97]
	v_mfma_f32_16x16x32_bf16 v[94:97], v[150:153], v[218:221], v[94:97]
	v_mfma_f32_16x16x32_bf16 v[86:89], v[164:167], v[218:221], v[86:89]
	v_mfma_f32_16x16x32_bf16 v[86:89], v[160:163], v[214:217], v[86:89]
	v_mfma_f32_16x16x32_bf16 v[70:73], v[160:163], v[222:225], v[70:73]
	v_mfma_f32_16x16x32_bf16 v[70:73], v[164:167], v[226:229], v[70:73]
	v_mfma_f32_16x16x32_bf16 v[78:81], v[150:153], v[226:229], v[78:81]
	v_mfma_f32_16x16x32_bf16 v[78:81], v[146:149], v[222:225], v[78:81]
	v_mfma_f32_16x16x32_bf16 v[122:125], v[168:171], v[184:187], v[122:125]
	v_mfma_f32_16x16x32_bf16 v[122:125], v[172:175], v[188:191], v[122:125]
	v_mfma_f32_16x16x32_bf16 v[114:117], v[180:183], v[188:191], v[114:117]
	v_mfma_f32_16x16x32_bf16 v[114:117], v[176:179], v[184:187], v[114:117]
	v_mfma_f32_16x16x32_bf16 v[98:101], v[176:179], v[206:209], v[98:101]
	v_mfma_f32_16x16x32_bf16 v[98:101], v[180:183], v[210:213], v[98:101]
	v_mfma_f32_16x16x32_bf16 v[106:109], v[172:175], v[210:213], v[106:109]
	v_mfma_f32_16x16x32_bf16 v[106:109], v[168:171], v[206:209], v[106:109]
	v_mfma_f32_16x16x32_bf16 v[90:93], v[168:171], v[214:217], v[90:93]
	v_mfma_f32_16x16x32_bf16 v[90:93], v[172:175], v[218:221], v[90:93]
	v_mfma_f32_16x16x32_bf16 v[82:85], v[180:183], v[218:221], v[82:85]
	v_mfma_f32_16x16x32_bf16 v[82:85], v[176:179], v[214:217], v[82:85]
	v_mfma_f32_16x16x32_bf16 v[66:69], v[176:179], v[222:225], v[66:69]
	v_mfma_f32_16x16x32_bf16 v[66:69], v[180:183], v[226:229], v[66:69]
	v_mfma_f32_16x16x32_bf16 v[74:77], v[172:175], v[226:229], v[74:77]
	v_mfma_f32_16x16x32_bf16 v[74:77], v[168:171], v[222:225], v[74:77]
	s_barrier
	s_add_i32 s22, s58, s29
	v_lshl_add_u64 v[230:231], v[230:231], 0, s[38:39]
	s_mov_b32 m0, s22
	ds_read_b128 v[184:187], v144 offset:49152
	ds_read_b128 v[188:191], v144 offset:50176
	ds_read_b128 v[206:209], v144 offset:51200
	ds_read_b128 v[210:213], v144 offset:52224
	ds_read_b128 v[214:217], v144 offset:53248
	ds_read_b128 v[218:221], v144 offset:54272
	ds_read_b128 v[222:225], v144 offset:55296
	ds_read_b128 v[226:229], v144 offset:56320
	global_load_lds_dwordx4 v[230:231], off
	s_add_i32 m0, s22, 0x2000
	s_add_u32 s22, s40, 0x40080
	v_lshl_add_u64 v[230:231], v[232:233], 0, s[38:39]
	s_addc_u32 s23, s41, 0
	s_add_i32 s40, s59, s29
	global_load_lds_dwordx4 v[230:231], off
	v_lshl_add_u64 v[230:231], s[22:23], 0, v[0:1]
	s_mov_b32 m0, s40
	s_nop 0
	global_load_lds_dwordx4 v[230:231], off
	v_lshl_add_u64 v[230:231], s[22:23], 0, v[130:131]
	s_add_i32 m0, s40, 0x2000
	s_nop 0
	global_load_lds_dwordx4 v[230:231], off
	v_lshl_add_u64 v[230:231], s[26:27], 0, v[134:135]
	s_mov_b32 m0, s49
	s_nop 0
	global_load_lds_dwordx4 v[230:231], off
	v_lshl_add_u64 v[230:231], s[26:27], 0, v[132:133]
	s_mov_b32 m0, s50
	s_nop 0
	global_load_lds_dwordx4 v[230:231], off
	s_waitcnt vmcnt(8) lgkmcnt(0)
	s_barrier
	v_mfma_f32_16x16x32_bf16 v[62:65], v[146:149], v[184:187], v[62:65]
	v_mfma_f32_16x16x32_bf16 v[62:65], v[150:153], v[188:191], v[62:65]
	v_mfma_f32_16x16x32_bf16 v[54:57], v[164:167], v[188:191], v[54:57]
	v_mfma_f32_16x16x32_bf16 v[54:57], v[160:163], v[184:187], v[54:57]
	v_mfma_f32_16x16x32_bf16 v[38:41], v[160:163], v[206:209], v[38:41]
	v_mfma_f32_16x16x32_bf16 v[38:41], v[164:167], v[210:213], v[38:41]
	v_mfma_f32_16x16x32_bf16 v[46:49], v[150:153], v[210:213], v[46:49]
	v_mfma_f32_16x16x32_bf16 v[46:49], v[146:149], v[206:209], v[46:49]
	v_mfma_f32_16x16x32_bf16 v[30:33], v[146:149], v[214:217], v[30:33]
	v_mfma_f32_16x16x32_bf16 v[30:33], v[150:153], v[218:221], v[30:33]
	v_mfma_f32_16x16x32_bf16 v[22:25], v[164:167], v[218:221], v[22:25]
	v_mfma_f32_16x16x32_bf16 v[22:25], v[160:163], v[214:217], v[22:25]
	v_mfma_f32_16x16x32_bf16 v[6:9], v[160:163], v[222:225], v[6:9]
	v_mfma_f32_16x16x32_bf16 v[6:9], v[164:167], v[226:229], v[6:9]
	v_mfma_f32_16x16x32_bf16 v[14:17], v[150:153], v[226:229], v[14:17]
	v_mfma_f32_16x16x32_bf16 v[14:17], v[146:149], v[222:225], v[14:17]
	v_mfma_f32_16x16x32_bf16 v[58:61], v[168:171], v[184:187], v[58:61]
	v_mfma_f32_16x16x32_bf16 v[58:61], v[172:175], v[188:191], v[58:61]
	v_mfma_f32_16x16x32_bf16 v[50:53], v[180:183], v[188:191], v[50:53]
	v_mfma_f32_16x16x32_bf16 v[50:53], v[176:179], v[184:187], v[50:53]
	v_mfma_f32_16x16x32_bf16 v[34:37], v[176:179], v[206:209], v[34:37]
	v_mfma_f32_16x16x32_bf16 v[34:37], v[180:183], v[210:213], v[34:37]
	v_mfma_f32_16x16x32_bf16 v[42:45], v[172:175], v[210:213], v[42:45]
	v_mfma_f32_16x16x32_bf16 v[42:45], v[168:171], v[206:209], v[42:45]
	v_mfma_f32_16x16x32_bf16 v[26:29], v[168:171], v[214:217], v[26:29]
	v_mfma_f32_16x16x32_bf16 v[26:29], v[172:175], v[218:221], v[26:29]
	v_mfma_f32_16x16x32_bf16 v[18:21], v[180:183], v[218:221], v[18:21]
	v_mfma_f32_16x16x32_bf16 v[18:21], v[176:179], v[214:217], v[18:21]
	v_mfma_f32_16x16x32_bf16 v[2:5], v[176:179], v[222:225], v[2:5]
	v_mfma_f32_16x16x32_bf16 v[2:5], v[180:183], v[226:229], v[2:5]
	v_mfma_f32_16x16x32_bf16 v[10:13], v[172:175], v[226:229], v[10:13]
	v_mfma_f32_16x16x32_bf16 v[10:13], v[168:171], v[222:225], v[10:13]
	s_barrier
	s_add_i32 s57, s57, 2
	s_add_u32 s55, s55, 0x100
	s_addc_u32 s56, s56, 0
	s_cmp_gt_u32 s57, 13
	s_mov_b64 s[22:23], s[24:25]
	s_cbranch_scc0 .LBB0_409
